# original 2/6 staging schedule kept; only saddr-form DMA, setprio removal and redundant wait removal (5 loops)
# speedup vs baseline: 1.0014x; 1.0014x over previous
; #define PG8_STAGE(bufoff, gbase, voff) do { _Pragma("unroll") for (int _i = 0; _i < 2; ++_i) \
;         __builtin_amdgcn_global_load_lds((const unsigned*)((const char*)(gbase) + (voff)[_i]), (PG8_LAS unsigned*)(lds + (bufoff) + ldsw + _i * 8192), 16, 0, 0); } while (0)
; #define PG8_STAGE_NT(bufoff, gbase, voff) do { _Pragma("unroll") for (int _i = 0; _i < 2; ++_i) \
;         __builtin_amdgcn_global_load_lds((const unsigned*)((const char*)(gbase) + (voff)[_i]), (PG8_LAS unsigned*)(lds + (bufoff) + ldsw + _i * 8192), 16, 0, PG8_B_AUX); } while (0)
; #define PG8_LDA(dst, b, h) do { _Pragma("unroll") for (int m = 0; m < 4; ++m) _Pragma("unroll") for (int k = 0; k < 2; ++k) dst[m][k] = *(const PG8_LAS bf16x8*)(lds + PG8_SA(b, h) + aoff + m * 2048 + k * 1024); } while (0)
; #define PG8_LDB(dst, b, h) do { _Pragma("unroll") for (int n = 0; n < 2; ++n) _Pragma("unroll") for (int k = 0; k < 2; ++k) dst[n][k] = *(const PG8_LAS bf16x8*)(lds + PG8_SB(b, h) + boff + n * 2048 + k * 1024); } while (0)
; #define PG8_WAIT_V(n) asm volatile("s_waitcnt vmcnt(" #n ")" ::: "memory")
; #define PG8_WAIT_L(n) asm volatile("s_waitcnt lgkmcnt(" #n ")" ::: "memory")
; #define PG8_BAR __builtin_amdgcn_s_barrier()
; #define PG8_SCHED __builtin_amdgcn_sched_barrier(0)
; template <class Epi, class Sched, bool ALIGN_EPI = false, bool SP2 = false>
; __device__ __forceinline__ void gemm_phase(PG8_LAS unsigned char* lds, const Gemm g, const Sched& S, const Epi& E, int wid) {
;     ...
;             const bool last = (t == nt - 2);
;             const char* a1 = cA + (size_t)(t + 1) * kstep;
;             const char* a2 = last ? nA : cA + (size_t)(t + 2) * kstep; const char* b2 = last ? nB : cB + (size_t)(t + 2) * kstep;
;             const char* a3 = a2 + kstep; const char* b3 = b2 + kstep;
;             if (last && has_next) S.a_ready(nxt);
;             if constexpr (SP2) {
;             PG8_LDB(B0, 0, 0); PG8_LDB(B1, 0, 1); PG8_SCHED; PG8_LDA(At, 0, 0); PG8_STAGE(PG8_SA(1, 1), a1 + hstepA, voffA);
;             PG8_WAIT_V(8); PG8_WAIT_L(0); PG8_BAR; PG8_MMA(0, 0, At, B0); PG8_MMA(0, 1, At, B1); PG8_BAR; PG8_SCHED;
;             PG8_LDA(At, 0, 1); PG8_STAGE_NT(PG8_SB(0, 0), b2, voffB); PG8_STAGE_NT(PG8_SB(0, 1), b2 + hstepB, voffB); PG8_STAGE(PG8_SA(0, 0), a2, voffA);
;             PG8_WAIT_V(8); PG8_WAIT_L(0); PG8_BAR; PG8_MMA(1, 0, At, B0); PG8_MMA(1, 1, At, B1); PG8_BAR; PG8_SCHED;
.LBB0_233:
	ds_read_b128 v[144:147], v155
	ds_read_b128 v[148:151], v155 offset:1024
	ds_read_b128 v[160:163], v155 offset:2048
	ds_read_b128 v[164:167], v155 offset:3072
	ds_read_b128 v[168:171], v156
	ds_read_b128 v[172:175], v156 offset:1024
	ds_read_b128 v[176:179], v156 offset:2048
	ds_read_b128 v[180:183], v156 offset:3072
	s_add_u32 s4, s48, 0x100
	s_addc_u32 s5, s49, 0
	s_add_u32 s98, s48, 0x80
	s_addc_u32 s99, s49, 0
	s_add_u32 s100, s48, 0x104080
	s_addc_u32 s101, s49, 0
	s_cmp_eq_u32 s66, 60
	s_cselect_b32 s53, s45, s5
	s_cselect_b32 s52, s44, s4
	s_cselect_b32 s51, s47, s65
	s_cselect_b32 s50, s46, s64
	s_add_i32 m0, s23, 0xc000
	ds_read_b128 v[184:187], v157
	ds_read_b128 v[188:191], v157 offset:1024
	ds_read_b128 v[192:195], v157 offset:2048
	ds_read_b128 v[196:199], v157 offset:3072
	ds_read_b128 v[200:203], v157 offset:4096
	ds_read_b128 v[204:207], v157 offset:5120
	ds_read_b128 v[208:211], v157 offset:6144
	ds_read_b128 v[212:215], v157 offset:7168
	global_load_lds_dwordx4 v134, s[100:101]
	s_add_i32 m0, s23, 0xe000
	s_nop 0
	global_load_lds_dwordx4 v130, s[100:101]
	s_waitcnt vmcnt(8)
	s_waitcnt lgkmcnt(0)
	s_barrier
	v_mfma_f32_16x16x32_bf16 v[112:115], v[144:147], v[184:187], v[112:115]
	v_mfma_f32_16x16x32_bf16 v[108:111], v[160:163], v[184:187], v[108:111]
	v_mfma_f32_16x16x32_bf16 v[104:107], v[144:147], v[192:195], v[104:107]
	v_mfma_f32_16x16x32_bf16 v[100:103], v[160:163], v[192:195], v[100:103]
	v_mfma_f32_16x16x32_bf16 v[92:95], v[144:147], v[200:203], v[92:95]
	v_mfma_f32_16x16x32_bf16 v[84:87], v[160:163], v[200:203], v[84:87]
	v_mfma_f32_16x16x32_bf16 v[76:79], v[144:147], v[208:211], v[76:79]
	v_mfma_f32_16x16x32_bf16 v[68:71], v[160:163], v[208:211], v[68:71]
	v_mfma_f32_16x16x32_bf16 v[112:115], v[148:151], v[188:191], v[112:115]
	v_mfma_f32_16x16x32_bf16 v[108:111], v[164:167], v[188:191], v[108:111]
	v_mfma_f32_16x16x32_bf16 v[104:107], v[148:151], v[196:199], v[104:107]
	v_mfma_f32_16x16x32_bf16 v[100:103], v[164:167], v[196:199], v[100:103]
	v_mfma_f32_16x16x32_bf16 v[92:95], v[148:151], v[204:207], v[92:95]
	v_mfma_f32_16x16x32_bf16 v[84:87], v[164:167], v[204:207], v[84:87]
	v_mfma_f32_16x16x32_bf16 v[76:79], v[148:151], v[212:215], v[76:79]
	v_mfma_f32_16x16x32_bf16 v[68:71], v[164:167], v[212:215], v[68:71]
	v_mfma_f32_16x16x32_bf16 v[124:127], v[168:171], v[184:187], v[124:127]
	v_mfma_f32_16x16x32_bf16 v[120:123], v[176:179], v[184:187], v[120:123]
	v_mfma_f32_16x16x32_bf16 v[116:119], v[168:171], v[192:195], v[116:119]
	v_mfma_f32_16x16x32_bf16 v[96:99], v[176:179], v[192:195], v[96:99]
	v_mfma_f32_16x16x32_bf16 v[88:91], v[168:171], v[200:203], v[88:91]
	v_mfma_f32_16x16x32_bf16 v[80:83], v[176:179], v[200:203], v[80:83]
	v_mfma_f32_16x16x32_bf16 v[72:75], v[168:171], v[208:211], v[72:75]
	v_mfma_f32_16x16x32_bf16 v[64:67], v[176:179], v[208:211], v[64:67]
	v_mfma_f32_16x16x32_bf16 v[124:127], v[172:175], v[188:191], v[124:127]
	v_mfma_f32_16x16x32_bf16 v[120:123], v[180:183], v[188:191], v[120:123]
	v_mfma_f32_16x16x32_bf16 v[116:119], v[172:175], v[196:199], v[116:119]
	v_mfma_f32_16x16x32_bf16 v[96:99], v[180:183], v[196:199], v[96:99]
	v_mfma_f32_16x16x32_bf16 v[88:91], v[172:175], v[204:207], v[88:91]
	v_mfma_f32_16x16x32_bf16 v[80:83], v[180:183], v[204:207], v[80:83]
	v_mfma_f32_16x16x32_bf16 v[72:75], v[172:175], v[212:215], v[72:75]
	v_mfma_f32_16x16x32_bf16 v[64:67], v[180:183], v[212:215], v[64:67]
	s_barrier
	s_add_i32 s48, s58, s17
	s_mov_b32 m0, s48
	ds_read_b128 v[184:187], v157 offset:16384
	ds_read_b128 v[188:191], v157 offset:17408
	ds_read_b128 v[192:195], v157 offset:18432
	ds_read_b128 v[196:199], v157 offset:19456
	ds_read_b128 v[200:203], v157 offset:20480
	ds_read_b128 v[204:207], v157 offset:21504
	ds_read_b128 v[208:211], v157 offset:22528
	ds_read_b128 v[212:215], v157 offset:23552
	global_load_lds_dwordx4 v132, s[50:51]
	s_add_i32 m0, s48, 0x2000
	s_add_u32 s48, s50, 0x104000
	s_addc_u32 s49, s51, 0
	s_add_i32 s67, s59, s17
	global_load_lds_dwordx4 v128, s[50:51]
	s_mov_b32 m0, s67
	s_nop 0
	global_load_lds_dwordx4 v132, s[48:49]
	s_add_i32 m0, s67, 0x2000
	s_nop 0
	global_load_lds_dwordx4 v128, s[48:49]
	s_mov_b32 m0, s23
	s_nop 0
	global_load_lds_dwordx4 v134, s[52:53]
	s_mov_b32 m0, s24
	s_nop 0
	global_load_lds_dwordx4 v130, s[52:53]
	s_waitcnt vmcnt(8)
	s_waitcnt lgkmcnt(0)
	s_barrier
	v_mfma_f32_16x16x32_bf16 v[60:63], v[144:147], v[184:187], v[60:63]
	v_mfma_f32_16x16x32_bf16 v[52:55], v[160:163], v[184:187], v[52:55]
	v_mfma_f32_16x16x32_bf16 v[44:47], v[144:147], v[192:195], v[44:47]
	v_mfma_f32_16x16x32_bf16 v[36:39], v[160:163], v[192:195], v[36:39]
	v_mfma_f32_16x16x32_bf16 v[28:31], v[144:147], v[200:203], v[28:31]
	v_mfma_f32_16x16x32_bf16 v[20:23], v[160:163], v[200:203], v[20:23]
	v_mfma_f32_16x16x32_bf16 v[12:15], v[144:147], v[208:211], v[12:15]
	v_mfma_f32_16x16x32_bf16 v[4:7], v[160:163], v[208:211], v[4:7]
	v_mfma_f32_16x16x32_bf16 v[60:63], v[148:151], v[188:191], v[60:63]
	v_mfma_f32_16x16x32_bf16 v[52:55], v[164:167], v[188:191], v[52:55]
	v_mfma_f32_16x16x32_bf16 v[44:47], v[148:151], v[196:199], v[44:47]
	v_mfma_f32_16x16x32_bf16 v[36:39], v[164:167], v[196:199], v[36:39]
	v_mfma_f32_16x16x32_bf16 v[28:31], v[148:151], v[204:207], v[28:31]
	v_mfma_f32_16x16x32_bf16 v[20:23], v[164:167], v[204:207], v[20:23]
	v_mfma_f32_16x16x32_bf16 v[12:15], v[148:151], v[212:215], v[12:15]
	v_mfma_f32_16x16x32_bf16 v[4:7], v[164:167], v[212:215], v[4:7]
	v_mfma_f32_16x16x32_bf16 v[56:59], v[168:171], v[184:187], v[56:59]
	v_mfma_f32_16x16x32_bf16 v[48:51], v[176:179], v[184:187], v[48:51]
	v_mfma_f32_16x16x32_bf16 v[40:43], v[168:171], v[192:195], v[40:43]
	v_mfma_f32_16x16x32_bf16 v[32:35], v[176:179], v[192:195], v[32:35]
	v_mfma_f32_16x16x32_bf16 v[24:27], v[168:171], v[200:203], v[24:27]
	v_mfma_f32_16x16x32_bf16 v[16:19], v[176:179], v[200:203], v[16:19]
	v_mfma_f32_16x16x32_bf16 v[8:11], v[168:171], v[208:211], v[8:11]
	v_mfma_f32_16x16x32_bf16 v[0:3], v[176:179], v[208:211], v[0:3]
	v_mfma_f32_16x16x32_bf16 v[56:59], v[172:175], v[188:191], v[56:59]
	v_mfma_f32_16x16x32_bf16 v[48:51], v[180:183], v[188:191], v[48:51]
	v_mfma_f32_16x16x32_bf16 v[40:43], v[172:175], v[196:199], v[40:43]
	v_mfma_f32_16x16x32_bf16 v[32:35], v[180:183], v[196:199], v[32:35]
	v_mfma_f32_16x16x32_bf16 v[24:27], v[172:175], v[204:207], v[24:27]
	v_mfma_f32_16x16x32_bf16 v[16:19], v[180:183], v[204:207], v[16:19]
	v_mfma_f32_16x16x32_bf16 v[8:11], v[172:175], v[212:215], v[8:11]
	v_mfma_f32_16x16x32_bf16 v[0:3], v[180:183], v[212:215], v[0:3]
	s_barrier
; #define PG8_STAGE(bufoff, gbase, voff) do { _Pragma("unroll") for (int _i = 0; _i < 2; ++_i) \
;         __builtin_amdgcn_global_load_lds((const unsigned*)((const char*)(gbase) + (voff)[_i]), (PG8_LAS unsigned*)(lds + (bufoff) + ldsw + _i * 8192), 16, 0, 0); } while (0)
; #define PG8_STAGE_NT(bufoff, gbase, voff) do { _Pragma("unroll") for (int _i = 0; _i < 2; ++_i) \
;         __builtin_amdgcn_global_load_lds((const unsigned*)((const char*)(gbase) + (voff)[_i]), (PG8_LAS unsigned*)(lds + (bufoff) + ldsw + _i * 8192), 16, 0, PG8_B_AUX); } while (0)
; #define PG8_LDA(dst, b, h) do { _Pragma("unroll") for (int m = 0; m < 4; ++m) _Pragma("unroll") for (int k = 0; k < 2; ++k) dst[m][k] = *(const PG8_LAS bf16x8*)(lds + PG8_SA(b, h) + aoff + m * 2048 + k * 1024); } while (0)
; #define PG8_LDB(dst, b, h) do { _Pragma("unroll") for (int n = 0; n < 2; ++n) _Pragma("unroll") for (int k = 0; k < 2; ++k) dst[n][k] = *(const PG8_LAS bf16x8*)(lds + PG8_SB(b, h) + boff + n * 2048 + k * 1024); } while (0)
; #define PG8_MMA(ai, bj, At, Bt) do { __builtin_amdgcn_s_setprio(1); _Pragma("unroll") for (int m = 0; m < 4; ++m) _Pragma("unroll") for (int n = 0; n < 2; ++n) _Pragma("unroll") for (int k = 0; k < 2; ++k) \
;         acc[ai][bj][m][n] = __builtin_amdgcn_mfma_f32_16x16x32_bf16(Bt[n][k], At[m][k], acc[ai][bj][m][n], 0, 0, 0); __builtin_amdgcn_s_setprio(0); } while (0)
; #define PG8_WAIT_V(n) asm volatile("s_waitcnt vmcnt(" #n ")" ::: "memory")
; #define PG8_WAIT_L(n) asm volatile("s_waitcnt lgkmcnt(" #n ")" ::: "memory")
; #define PG8_BAR __builtin_amdgcn_s_barrier()
; #define PG8_SCHED __builtin_amdgcn_sched_barrier(0)
; template <class Epi, class Sched, bool ALIGN_EPI = false, bool SP2 = false>
; __device__ __forceinline__ void gemm_phase(PG8_LAS unsigned char* lds, const Gemm g, const Sched& S, const Epi& E, int wid) {
;     ...
;             PG8_LDB(B0, 1, 0); PG8_LDB(B1, 1, 1); PG8_SCHED; PG8_LDA(At, 1, 0); PG8_STAGE(PG8_SA(0, 1), a2 + hstepA, voffA);
;             PG8_WAIT_V(8); PG8_WAIT_L(0); PG8_BAR; PG8_MMA(0, 0, At, B0); PG8_MMA(0, 1, At, B1); PG8_BAR; PG8_SCHED;
;             PG8_LDA(At, 1, 1); PG8_STAGE_NT(PG8_SB(1, 0), b3, voffB); PG8_STAGE_NT(PG8_SB(1, 1), b3 + hstepB, voffB); PG8_STAGE(PG8_SA(1, 0), a3, voffA);
;             PG8_WAIT_V(8); PG8_WAIT_L(0); PG8_BAR; PG8_MMA(1, 0, At, B0); PG8_MMA(1, 1, At, B1); PG8_BAR; PG8_SCHED;
	s_add_i32 s67, 0, 0x18000
	v_add_u32_e32 v159, s67, v153
	s_add_i32 s68, 0, 0x1c000
	ds_read_b128 v[144:147], v159
	ds_read_b128 v[148:151], v159 offset:1024
	ds_read_b128 v[160:163], v159 offset:2048
	ds_read_b128 v[164:167], v159 offset:3072
	v_add_u32_e32 v159, s68, v153
	ds_read_b128 v[168:171], v159
	ds_read_b128 v[172:175], v159 offset:1024
	ds_read_b128 v[176:179], v159 offset:2048
	ds_read_b128 v[180:183], v159 offset:3072
	s_add_u32 s48, s52, 0x104000
	s_addc_u32 s49, s53, 0
	s_mov_b32 m0, s25
	ds_read_b128 v[184:187], v157 offset:32768
	ds_read_b128 v[188:191], v157 offset:33792
	ds_read_b128 v[192:195], v157 offset:34816
	ds_read_b128 v[196:199], v157 offset:35840
	ds_read_b128 v[200:203], v157 offset:36864
	ds_read_b128 v[204:207], v157 offset:37888
	ds_read_b128 v[208:211], v157 offset:38912
	ds_read_b128 v[212:215], v157 offset:39936
	global_load_lds_dwordx4 v134, s[48:49]
	s_mov_b32 m0, s29
	s_nop 0
	global_load_lds_dwordx4 v130, s[48:49]
	s_waitcnt vmcnt(8)
	s_waitcnt lgkmcnt(0)
	s_barrier
	v_mfma_f32_16x16x32_bf16 v[112:115], v[144:147], v[184:187], v[112:115]
	v_mfma_f32_16x16x32_bf16 v[108:111], v[160:163], v[184:187], v[108:111]
	v_mfma_f32_16x16x32_bf16 v[104:107], v[144:147], v[192:195], v[104:107]
	v_mfma_f32_16x16x32_bf16 v[100:103], v[160:163], v[192:195], v[100:103]
	v_mfma_f32_16x16x32_bf16 v[92:95], v[144:147], v[200:203], v[92:95]
	v_mfma_f32_16x16x32_bf16 v[84:87], v[160:163], v[200:203], v[84:87]
	v_mfma_f32_16x16x32_bf16 v[76:79], v[144:147], v[208:211], v[76:79]
	v_mfma_f32_16x16x32_bf16 v[68:71], v[160:163], v[208:211], v[68:71]
	v_mfma_f32_16x16x32_bf16 v[112:115], v[148:151], v[188:191], v[112:115]
	v_mfma_f32_16x16x32_bf16 v[108:111], v[164:167], v[188:191], v[108:111]
	v_mfma_f32_16x16x32_bf16 v[104:107], v[148:151], v[196:199], v[104:107]
	v_mfma_f32_16x16x32_bf16 v[100:103], v[164:167], v[196:199], v[100:103]
	v_mfma_f32_16x16x32_bf16 v[92:95], v[148:151], v[204:207], v[92:95]
	v_mfma_f32_16x16x32_bf16 v[84:87], v[164:167], v[204:207], v[84:87]
	v_mfma_f32_16x16x32_bf16 v[76:79], v[148:151], v[212:215], v[76:79]
	v_mfma_f32_16x16x32_bf16 v[68:71], v[164:167], v[212:215], v[68:71]
	v_mfma_f32_16x16x32_bf16 v[124:127], v[168:171], v[184:187], v[124:127]
	v_mfma_f32_16x16x32_bf16 v[120:123], v[176:179], v[184:187], v[120:123]
	v_mfma_f32_16x16x32_bf16 v[116:119], v[168:171], v[192:195], v[116:119]
	v_mfma_f32_16x16x32_bf16 v[96:99], v[176:179], v[192:195], v[96:99]
	v_mfma_f32_16x16x32_bf16 v[88:91], v[168:171], v[200:203], v[88:91]
	v_mfma_f32_16x16x32_bf16 v[80:83], v[176:179], v[200:203], v[80:83]
	v_mfma_f32_16x16x32_bf16 v[72:75], v[168:171], v[208:211], v[72:75]
	v_mfma_f32_16x16x32_bf16 v[64:67], v[176:179], v[208:211], v[64:67]
	v_mfma_f32_16x16x32_bf16 v[124:127], v[172:175], v[188:191], v[124:127]
	v_mfma_f32_16x16x32_bf16 v[120:123], v[180:183], v[188:191], v[120:123]
	v_mfma_f32_16x16x32_bf16 v[116:119], v[172:175], v[196:199], v[116:119]
	v_mfma_f32_16x16x32_bf16 v[96:99], v[180:183], v[196:199], v[96:99]
	v_mfma_f32_16x16x32_bf16 v[88:91], v[172:175], v[204:207], v[88:91]
	v_mfma_f32_16x16x32_bf16 v[80:83], v[180:183], v[204:207], v[80:83]
	v_mfma_f32_16x16x32_bf16 v[72:75], v[172:175], v[212:215], v[72:75]
	v_mfma_f32_16x16x32_bf16 v[64:67], v[180:183], v[212:215], v[64:67]
	s_barrier
	s_add_i32 s48, s67, s17
	s_mov_b32 m0, s48
	s_add_u32 s98, s50, 0x80
	s_addc_u32 s99, s51, 0
	ds_read_b128 v[184:187], v157 offset:49152
	ds_read_b128 v[188:191], v157 offset:50176
	ds_read_b128 v[192:195], v157 offset:51200
	ds_read_b128 v[196:199], v157 offset:52224
	ds_read_b128 v[200:203], v157 offset:53248
	ds_read_b128 v[204:207], v157 offset:54272
	ds_read_b128 v[208:211], v157 offset:55296
	ds_read_b128 v[212:215], v157 offset:56320
	global_load_lds_dwordx4 v132, s[98:99]
	s_add_i32 m0, s48, 0x2000
	s_add_u32 s48, s50, 0x104080
	s_addc_u32 s49, s51, 0
	s_add_i32 s50, s68, s17
	global_load_lds_dwordx4 v128, s[98:99]
	s_mov_b32 m0, s50
	s_nop 0
	global_load_lds_dwordx4 v132, s[48:49]
	s_add_i32 m0, s50, 0x2000
	s_nop 0
	global_load_lds_dwordx4 v128, s[48:49]
	s_add_u32 s100, s52, 0x80
	s_addc_u32 s101, s53, 0
	s_mov_b32 m0, s55
	s_nop 0
	global_load_lds_dwordx4 v134, s[100:101]
	s_mov_b32 m0, s56
	s_nop 0
	global_load_lds_dwordx4 v130, s[100:101]
	s_waitcnt vmcnt(8)
	s_waitcnt lgkmcnt(0)
	s_barrier
	v_mfma_f32_16x16x32_bf16 v[60:63], v[144:147], v[184:187], v[60:63]
	v_mfma_f32_16x16x32_bf16 v[52:55], v[160:163], v[184:187], v[52:55]
	v_mfma_f32_16x16x32_bf16 v[44:47], v[144:147], v[192:195], v[44:47]
	v_mfma_f32_16x16x32_bf16 v[36:39], v[160:163], v[192:195], v[36:39]
	v_mfma_f32_16x16x32_bf16 v[28:31], v[144:147], v[200:203], v[28:31]
	v_mfma_f32_16x16x32_bf16 v[20:23], v[160:163], v[200:203], v[20:23]
	v_mfma_f32_16x16x32_bf16 v[12:15], v[144:147], v[208:211], v[12:15]
	v_mfma_f32_16x16x32_bf16 v[4:7], v[160:163], v[208:211], v[4:7]
	v_mfma_f32_16x16x32_bf16 v[60:63], v[148:151], v[188:191], v[60:63]
	v_mfma_f32_16x16x32_bf16 v[52:55], v[164:167], v[188:191], v[52:55]
	v_mfma_f32_16x16x32_bf16 v[44:47], v[148:151], v[196:199], v[44:47]
	v_mfma_f32_16x16x32_bf16 v[36:39], v[164:167], v[196:199], v[36:39]
	v_mfma_f32_16x16x32_bf16 v[28:31], v[148:151], v[204:207], v[28:31]
	v_mfma_f32_16x16x32_bf16 v[20:23], v[164:167], v[204:207], v[20:23]
	v_mfma_f32_16x16x32_bf16 v[12:15], v[148:151], v[212:215], v[12:15]
	v_mfma_f32_16x16x32_bf16 v[4:7], v[164:167], v[212:215], v[4:7]
	v_mfma_f32_16x16x32_bf16 v[56:59], v[168:171], v[184:187], v[56:59]
	v_mfma_f32_16x16x32_bf16 v[48:51], v[176:179], v[184:187], v[48:51]
	v_mfma_f32_16x16x32_bf16 v[40:43], v[168:171], v[192:195], v[40:43]
	v_mfma_f32_16x16x32_bf16 v[32:35], v[176:179], v[192:195], v[32:35]
	v_mfma_f32_16x16x32_bf16 v[24:27], v[168:171], v[200:203], v[24:27]
	v_mfma_f32_16x16x32_bf16 v[16:19], v[176:179], v[200:203], v[16:19]
	v_mfma_f32_16x16x32_bf16 v[8:11], v[168:171], v[208:211], v[8:11]
	v_mfma_f32_16x16x32_bf16 v[0:3], v[176:179], v[208:211], v[0:3]
	v_mfma_f32_16x16x32_bf16 v[56:59], v[172:175], v[188:191], v[56:59]
	v_mfma_f32_16x16x32_bf16 v[48:51], v[180:183], v[188:191], v[48:51]
	v_mfma_f32_16x16x32_bf16 v[40:43], v[172:175], v[196:199], v[40:43]
	v_mfma_f32_16x16x32_bf16 v[32:35], v[180:183], v[196:199], v[32:35]
	v_mfma_f32_16x16x32_bf16 v[24:27], v[172:175], v[204:207], v[24:27]
	v_mfma_f32_16x16x32_bf16 v[16:19], v[180:183], v[204:207], v[16:19]
	v_mfma_f32_16x16x32_bf16 v[8:11], v[172:175], v[212:215], v[8:11]
	v_mfma_f32_16x16x32_bf16 v[0:3], v[180:183], v[212:215], v[0:3]
	s_barrier
	s_add_i32 s66, s66, 2
	s_add_u32 s64, s64, 0x100
	s_addc_u32 s65, s65, 0
	s_cmp_gt_u32 s66, 61
	s_mov_b64 s[48:49], s[4:5]
	s_cbranch_scc0 .LBB0_233
	s_and_b64 vcc, exec, s[42:43]
	s_cbranch_vccz .LBB0_236
	s_barrier

; #define PG8_STAGE(bufoff, gbase, voff) do { _Pragma("unroll") for (int _i = 0; _i < 2; ++_i) \
;         __builtin_amdgcn_global_load_lds((const unsigned*)((const char*)(gbase) + (voff)[_i]), (PG8_LAS unsigned*)(lds + (bufoff) + ldsw + _i * 8192), 16, 0, 0); } while (0)
; #define PG8_STAGE_NT(bufoff, gbase, voff) do { _Pragma("unroll") for (int _i = 0; _i < 2; ++_i) \
;         __builtin_amdgcn_global_load_lds((const unsigned*)((const char*)(gbase) + (voff)[_i]), (PG8_LAS unsigned*)(lds + (bufoff) + ldsw + _i * 8192), 16, 0, PG8_B_AUX); } while (0)
; #define PG8_LDA(dst, b, h) do { _Pragma("unroll") for (int m = 0; m < 4; ++m) _Pragma("unroll") for (int k = 0; k < 2; ++k) dst[m][k] = *(const PG8_LAS bf16x8*)(lds + PG8_SA(b, h) + aoff + m * 2048 + k * 1024); } while (0)
; #define PG8_LDB(dst, b, h) do { _Pragma("unroll") for (int n = 0; n < 2; ++n) _Pragma("unroll") for (int k = 0; k < 2; ++k) dst[n][k] = *(const PG8_LAS bf16x8*)(lds + PG8_SB(b, h) + boff + n * 2048 + k * 1024); } while (0)
; #define PG8_WAIT_V(n) asm volatile("s_waitcnt vmcnt(" #n ")" ::: "memory")
; #define PG8_WAIT_L(n) asm volatile("s_waitcnt lgkmcnt(" #n ")" ::: "memory")
; #define PG8_BAR __builtin_amdgcn_s_barrier()
; #define PG8_SCHED __builtin_amdgcn_sched_barrier(0)
; template <class Epi, class Sched, bool ALIGN_EPI = false, bool SP2 = false>
; __device__ __forceinline__ void gemm_phase(PG8_LAS unsigned char* lds, const Gemm g, const Sched& S, const Epi& E, int wid) {
;     ...
;             const bool last = (t == nt - 2);
;             const char* a1 = cA + (size_t)(t + 1) * kstep;
;             const char* a2 = last ? nA : cA + (size_t)(t + 2) * kstep; const char* b2 = last ? nB : cB + (size_t)(t + 2) * kstep;
;             const char* a3 = a2 + kstep; const char* b3 = b2 + kstep;
;             if (last && has_next) S.a_ready(nxt);
;             if constexpr (SP2) {
;             PG8_LDB(B0, 0, 0); PG8_LDB(B1, 0, 1); PG8_SCHED; PG8_LDA(At, 0, 0); PG8_STAGE(PG8_SA(1, 1), a1 + hstepA, voffA);
;             PG8_WAIT_V(8); PG8_WAIT_L(0); PG8_BAR; PG8_MMA(0, 0, At, B0); PG8_MMA(0, 1, At, B1); PG8_BAR; PG8_SCHED;
;             PG8_LDA(At, 0, 1); PG8_STAGE_NT(PG8_SB(0, 0), b2, voffB); PG8_STAGE_NT(PG8_SB(0, 1), b2 + hstepB, voffB); PG8_STAGE(PG8_SA(0, 0), a2, voffA);
;             PG8_WAIT_V(8); PG8_WAIT_L(0); PG8_BAR; PG8_MMA(1, 0, At, B0); PG8_MMA(1, 1, At, B1); PG8_BAR; PG8_SCHED;
.LBB0_317:
	ds_read_b128 v[128:131], v205
	ds_read_b128 v[132:135], v205 offset:1024
	ds_read_b128 v[136:139], v205 offset:2048
	ds_read_b128 v[140:143], v205 offset:3072
	ds_read_b128 v[144:147], v206
	ds_read_b128 v[148:151], v206 offset:1024
	ds_read_b128 v[152:155], v206 offset:2048
	ds_read_b128 v[156:159], v206 offset:3072
	s_add_u32 s48, s46, 0x100
	s_addc_u32 s49, s47, 0
	s_add_u32 s98, s46, 0x80
	s_addc_u32 s99, s47, 0
	s_add_u32 s100, s46, 0x2b4080
	s_addc_u32 s101, s47, 0
	s_cmpk_eq_i32 s64, 0xa8
	s_cselect_b32 s53, s7, s49
	s_cselect_b32 s52, s6, s48
	s_cselect_b32 s51, s45, s63
	s_cselect_b32 s50, s44, s62
	s_add_i32 m0, s19, 0xc000
	ds_read_b128 v[160:163], v207
	ds_read_b128 v[164:167], v207 offset:1024
	ds_read_b128 v[184:187], v207 offset:2048
	ds_read_b128 v[188:191], v207 offset:3072
	ds_read_b128 v[192:195], v207 offset:4096
	ds_read_b128 v[196:199], v207 offset:5120
	ds_read_b128 v[210:213], v207 offset:6144
	ds_read_b128 v[214:217], v207 offset:7168
	global_load_lds_dwordx4 v168, s[100:101]
	s_add_i32 m0, s19, 0xe000
	s_nop 0
	global_load_lds_dwordx4 v172, s[100:101]
	s_waitcnt vmcnt(8)
	s_waitcnt lgkmcnt(0)
	s_barrier
	v_mfma_f32_16x16x32_bf16 v[124:127], v[128:131], v[160:163], v[124:127]
	v_mfma_f32_16x16x32_bf16 v[120:123], v[136:139], v[160:163], v[120:123]
	v_mfma_f32_16x16x32_bf16 v[116:119], v[128:131], v[184:187], v[116:119]
	v_mfma_f32_16x16x32_bf16 v[112:115], v[136:139], v[184:187], v[112:115]
	v_mfma_f32_16x16x32_bf16 v[92:95], v[128:131], v[192:195], v[92:95]
	v_mfma_f32_16x16x32_bf16 v[88:91], v[136:139], v[192:195], v[88:91]
	v_mfma_f32_16x16x32_bf16 v[76:79], v[128:131], v[210:213], v[76:79]
	v_mfma_f32_16x16x32_bf16 v[72:75], v[136:139], v[210:213], v[72:75]
	v_mfma_f32_16x16x32_bf16 v[124:127], v[132:135], v[164:167], v[124:127]
	v_mfma_f32_16x16x32_bf16 v[120:123], v[140:143], v[164:167], v[120:123]
	v_mfma_f32_16x16x32_bf16 v[116:119], v[132:135], v[188:191], v[116:119]
	v_mfma_f32_16x16x32_bf16 v[112:115], v[140:143], v[188:191], v[112:115]
	v_mfma_f32_16x16x32_bf16 v[92:95], v[132:135], v[196:199], v[92:95]
	v_mfma_f32_16x16x32_bf16 v[88:91], v[140:143], v[196:199], v[88:91]
	v_mfma_f32_16x16x32_bf16 v[76:79], v[132:135], v[214:217], v[76:79]
	v_mfma_f32_16x16x32_bf16 v[72:75], v[140:143], v[214:217], v[72:75]
	v_mfma_f32_16x16x32_bf16 v[108:111], v[144:147], v[160:163], v[108:111]
	v_mfma_f32_16x16x32_bf16 v[104:107], v[152:155], v[160:163], v[104:107]
	v_mfma_f32_16x16x32_bf16 v[100:103], v[144:147], v[184:187], v[100:103]
	v_mfma_f32_16x16x32_bf16 v[96:99], v[152:155], v[184:187], v[96:99]
	v_mfma_f32_16x16x32_bf16 v[84:87], v[144:147], v[192:195], v[84:87]
	v_mfma_f32_16x16x32_bf16 v[80:83], v[152:155], v[192:195], v[80:83]
	v_mfma_f32_16x16x32_bf16 v[68:71], v[144:147], v[210:213], v[68:71]
	v_mfma_f32_16x16x32_bf16 v[64:67], v[152:155], v[210:213], v[64:67]
	v_mfma_f32_16x16x32_bf16 v[108:111], v[148:151], v[164:167], v[108:111]
	v_mfma_f32_16x16x32_bf16 v[104:107], v[156:159], v[164:167], v[104:107]
	v_mfma_f32_16x16x32_bf16 v[100:103], v[148:151], v[188:191], v[100:103]
	v_mfma_f32_16x16x32_bf16 v[96:99], v[156:159], v[188:191], v[96:99]
	v_mfma_f32_16x16x32_bf16 v[84:87], v[148:151], v[196:199], v[84:87]
	v_mfma_f32_16x16x32_bf16 v[80:83], v[156:159], v[196:199], v[80:83]
	v_mfma_f32_16x16x32_bf16 v[68:71], v[148:151], v[214:217], v[68:71]
	v_mfma_f32_16x16x32_bf16 v[64:67], v[156:159], v[214:217], v[64:67]
	s_barrier
	s_add_i32 s46, s57, s17
	s_mov_b32 m0, s46
	ds_read_b128 v[160:163], v207 offset:16384
	ds_read_b128 v[164:167], v207 offset:17408
	ds_read_b128 v[184:187], v207 offset:18432
	ds_read_b128 v[188:191], v207 offset:19456
	ds_read_b128 v[192:195], v207 offset:20480
	ds_read_b128 v[196:199], v207 offset:21504
	ds_read_b128 v[210:213], v207 offset:22528
	ds_read_b128 v[214:217], v207 offset:23552
	global_load_lds_dwordx4 v170, s[50:51]
	s_add_i32 m0, s46, 0x2000
	s_add_u32 s46, s50, 0x2b4000
	s_addc_u32 s47, s51, 0
	s_add_i32 s65, s58, s17
	global_load_lds_dwordx4 v174, s[50:51]
	s_mov_b32 m0, s65
	s_nop 0
	global_load_lds_dwordx4 v170, s[46:47]
	s_add_i32 m0, s65, 0x2000
	s_nop 0
	global_load_lds_dwordx4 v174, s[46:47]
	s_mov_b32 m0, s19
	s_nop 0
	global_load_lds_dwordx4 v168, s[52:53]
	s_mov_b32 m0, s22
	s_nop 0
	global_load_lds_dwordx4 v172, s[52:53]
	s_waitcnt vmcnt(8)
	s_waitcnt lgkmcnt(0)
	s_barrier
	v_mfma_f32_16x16x32_bf16 v[60:63], v[128:131], v[160:163], v[60:63]
	v_mfma_f32_16x16x32_bf16 v[56:59], v[136:139], v[160:163], v[56:59]
	v_mfma_f32_16x16x32_bf16 v[44:47], v[128:131], v[184:187], v[44:47]
	v_mfma_f32_16x16x32_bf16 v[40:43], v[136:139], v[184:187], v[40:43]
	v_mfma_f32_16x16x32_bf16 v[28:31], v[128:131], v[192:195], v[28:31]
	v_mfma_f32_16x16x32_bf16 v[24:27], v[136:139], v[192:195], v[24:27]
	v_mfma_f32_16x16x32_bf16 v[12:15], v[128:131], v[210:213], v[12:15]
	v_mfma_f32_16x16x32_bf16 v[8:11], v[136:139], v[210:213], v[8:11]
	v_mfma_f32_16x16x32_bf16 v[60:63], v[132:135], v[164:167], v[60:63]
	v_mfma_f32_16x16x32_bf16 v[56:59], v[140:143], v[164:167], v[56:59]
	v_mfma_f32_16x16x32_bf16 v[44:47], v[132:135], v[188:191], v[44:47]
	v_mfma_f32_16x16x32_bf16 v[40:43], v[140:143], v[188:191], v[40:43]
	v_mfma_f32_16x16x32_bf16 v[28:31], v[132:135], v[196:199], v[28:31]
	v_mfma_f32_16x16x32_bf16 v[24:27], v[140:143], v[196:199], v[24:27]
	v_mfma_f32_16x16x32_bf16 v[12:15], v[132:135], v[214:217], v[12:15]
	v_mfma_f32_16x16x32_bf16 v[8:11], v[140:143], v[214:217], v[8:11]
	v_mfma_f32_16x16x32_bf16 v[52:55], v[144:147], v[160:163], v[52:55]
	v_mfma_f32_16x16x32_bf16 v[48:51], v[152:155], v[160:163], v[48:51]
	v_mfma_f32_16x16x32_bf16 v[36:39], v[144:147], v[184:187], v[36:39]
	v_mfma_f32_16x16x32_bf16 v[32:35], v[152:155], v[184:187], v[32:35]
	v_mfma_f32_16x16x32_bf16 v[20:23], v[144:147], v[192:195], v[20:23]
	v_mfma_f32_16x16x32_bf16 v[16:19], v[152:155], v[192:195], v[16:19]
	v_mfma_f32_16x16x32_bf16 v[4:7], v[144:147], v[210:213], v[4:7]
	v_mfma_f32_16x16x32_bf16 v[0:3], v[152:155], v[210:213], v[0:3]
	v_mfma_f32_16x16x32_bf16 v[52:55], v[148:151], v[164:167], v[52:55]
	v_mfma_f32_16x16x32_bf16 v[48:51], v[156:159], v[164:167], v[48:51]
	v_mfma_f32_16x16x32_bf16 v[36:39], v[148:151], v[188:191], v[36:39]
	v_mfma_f32_16x16x32_bf16 v[32:35], v[156:159], v[188:191], v[32:35]
	v_mfma_f32_16x16x32_bf16 v[20:23], v[148:151], v[196:199], v[20:23]
	v_mfma_f32_16x16x32_bf16 v[16:19], v[156:159], v[196:199], v[16:19]
	v_mfma_f32_16x16x32_bf16 v[4:7], v[148:151], v[214:217], v[4:7]
	v_mfma_f32_16x16x32_bf16 v[0:3], v[156:159], v[214:217], v[0:3]
	s_barrier
; #define PG8_STAGE(bufoff, gbase, voff) do { _Pragma("unroll") for (int _i = 0; _i < 2; ++_i) \
;         __builtin_amdgcn_global_load_lds((const unsigned*)((const char*)(gbase) + (voff)[_i]), (PG8_LAS unsigned*)(lds + (bufoff) + ldsw + _i * 8192), 16, 0, 0); } while (0)
; #define PG8_STAGE_NT(bufoff, gbase, voff) do { _Pragma("unroll") for (int _i = 0; _i < 2; ++_i) \
;         __builtin_amdgcn_global_load_lds((const unsigned*)((const char*)(gbase) + (voff)[_i]), (PG8_LAS unsigned*)(lds + (bufoff) + ldsw + _i * 8192), 16, 0, PG8_B_AUX); } while (0)
; #define PG8_LDA(dst, b, h) do { _Pragma("unroll") for (int m = 0; m < 4; ++m) _Pragma("unroll") for (int k = 0; k < 2; ++k) dst[m][k] = *(const PG8_LAS bf16x8*)(lds + PG8_SA(b, h) + aoff + m * 2048 + k * 1024); } while (0)
; #define PG8_LDB(dst, b, h) do { _Pragma("unroll") for (int n = 0; n < 2; ++n) _Pragma("unroll") for (int k = 0; k < 2; ++k) dst[n][k] = *(const PG8_LAS bf16x8*)(lds + PG8_SB(b, h) + boff + n * 2048 + k * 1024); } while (0)
; #define PG8_MMA(ai, bj, At, Bt) do { __builtin_amdgcn_s_setprio(1); _Pragma("unroll") for (int m = 0; m < 4; ++m) _Pragma("unroll") for (int n = 0; n < 2; ++n) _Pragma("unroll") for (int k = 0; k < 2; ++k) \
;         acc[ai][bj][m][n] = __builtin_amdgcn_mfma_f32_16x16x32_bf16(Bt[n][k], At[m][k], acc[ai][bj][m][n], 0, 0, 0); __builtin_amdgcn_s_setprio(0); } while (0)
; #define PG8_WAIT_V(n) asm volatile("s_waitcnt vmcnt(" #n ")" ::: "memory")
; #define PG8_WAIT_L(n) asm volatile("s_waitcnt lgkmcnt(" #n ")" ::: "memory")
; #define PG8_BAR __builtin_amdgcn_s_barrier()
; #define PG8_SCHED __builtin_amdgcn_sched_barrier(0)
; template <class Epi, class Sched, bool ALIGN_EPI = false, bool SP2 = false>
; __device__ __forceinline__ void gemm_phase(PG8_LAS unsigned char* lds, const Gemm g, const Sched& S, const Epi& E, int wid) {
;     ...
;             PG8_LDB(B0, 1, 0); PG8_LDB(B1, 1, 1); PG8_SCHED; PG8_LDA(At, 1, 0); PG8_STAGE(PG8_SA(0, 1), a2 + hstepA, voffA);
;             PG8_WAIT_V(8); PG8_WAIT_L(0); PG8_BAR; PG8_MMA(0, 0, At, B0); PG8_MMA(0, 1, At, B1); PG8_BAR; PG8_SCHED;
;             PG8_LDA(At, 1, 1); PG8_STAGE_NT(PG8_SB(1, 0), b3, voffB); PG8_STAGE_NT(PG8_SB(1, 1), b3 + hstepB, voffB); PG8_STAGE(PG8_SA(1, 0), a3, voffA);
;             PG8_WAIT_V(8); PG8_WAIT_L(0); PG8_BAR; PG8_MMA(1, 0, At, B0); PG8_MMA(1, 1, At, B1); PG8_BAR; PG8_SCHED;
	s_add_i32 s65, 0, 0x18000
	v_add_u32_e32 v140, s65, v203
	s_add_i32 s66, 0, 0x1c000
	ds_read_b128 v[128:131], v140
	ds_read_b128 v[132:135], v140 offset:1024
	ds_read_b128 v[136:139], v140 offset:2048
	ds_read_b128 v[140:143], v140 offset:3072
	v_add_u32_e32 v156, s66, v203
	ds_read_b128 v[144:147], v156
	ds_read_b128 v[148:151], v156 offset:1024
	ds_read_b128 v[152:155], v156 offset:2048
	ds_read_b128 v[156:159], v156 offset:3072
	s_add_u32 s46, s52, 0x2b4000
	s_addc_u32 s47, s53, 0
	s_mov_b32 m0, s23
	ds_read_b128 v[160:163], v207 offset:32768
	ds_read_b128 v[164:167], v207 offset:33792
	ds_read_b128 v[184:187], v207 offset:34816
	ds_read_b128 v[188:191], v207 offset:35840
	ds_read_b128 v[192:195], v207 offset:36864
	ds_read_b128 v[196:199], v207 offset:37888
	ds_read_b128 v[210:213], v207 offset:38912
	ds_read_b128 v[214:217], v207 offset:39936
	global_load_lds_dwordx4 v168, s[46:47]
	s_mov_b32 m0, s24
	s_nop 0
	global_load_lds_dwordx4 v172, s[46:47]
	s_waitcnt vmcnt(8)
	s_waitcnt lgkmcnt(0)
	s_barrier
	v_mfma_f32_16x16x32_bf16 v[124:127], v[128:131], v[160:163], v[124:127]
	v_mfma_f32_16x16x32_bf16 v[120:123], v[136:139], v[160:163], v[120:123]
	v_mfma_f32_16x16x32_bf16 v[116:119], v[128:131], v[184:187], v[116:119]
	v_mfma_f32_16x16x32_bf16 v[112:115], v[136:139], v[184:187], v[112:115]
	v_mfma_f32_16x16x32_bf16 v[92:95], v[128:131], v[192:195], v[92:95]
	v_mfma_f32_16x16x32_bf16 v[88:91], v[136:139], v[192:195], v[88:91]
	v_mfma_f32_16x16x32_bf16 v[76:79], v[128:131], v[210:213], v[76:79]
	v_mfma_f32_16x16x32_bf16 v[72:75], v[136:139], v[210:213], v[72:75]
	v_mfma_f32_16x16x32_bf16 v[124:127], v[132:135], v[164:167], v[124:127]
	v_mfma_f32_16x16x32_bf16 v[120:123], v[140:143], v[164:167], v[120:123]
	v_mfma_f32_16x16x32_bf16 v[116:119], v[132:135], v[188:191], v[116:119]
	v_mfma_f32_16x16x32_bf16 v[112:115], v[140:143], v[188:191], v[112:115]
	v_mfma_f32_16x16x32_bf16 v[92:95], v[132:135], v[196:199], v[92:95]
	v_mfma_f32_16x16x32_bf16 v[88:91], v[140:143], v[196:199], v[88:91]
	v_mfma_f32_16x16x32_bf16 v[76:79], v[132:135], v[214:217], v[76:79]
	v_mfma_f32_16x16x32_bf16 v[72:75], v[140:143], v[214:217], v[72:75]
	v_mfma_f32_16x16x32_bf16 v[108:111], v[144:147], v[160:163], v[108:111]
	v_mfma_f32_16x16x32_bf16 v[104:107], v[152:155], v[160:163], v[104:107]
	v_mfma_f32_16x16x32_bf16 v[100:103], v[144:147], v[184:187], v[100:103]
	v_mfma_f32_16x16x32_bf16 v[96:99], v[152:155], v[184:187], v[96:99]
	v_mfma_f32_16x16x32_bf16 v[84:87], v[144:147], v[192:195], v[84:87]
	v_mfma_f32_16x16x32_bf16 v[80:83], v[152:155], v[192:195], v[80:83]
	v_mfma_f32_16x16x32_bf16 v[68:71], v[144:147], v[210:213], v[68:71]
	v_mfma_f32_16x16x32_bf16 v[64:67], v[152:155], v[210:213], v[64:67]
	v_mfma_f32_16x16x32_bf16 v[108:111], v[148:151], v[164:167], v[108:111]
	v_mfma_f32_16x16x32_bf16 v[104:107], v[156:159], v[164:167], v[104:107]
	v_mfma_f32_16x16x32_bf16 v[100:103], v[148:151], v[188:191], v[100:103]
	v_mfma_f32_16x16x32_bf16 v[96:99], v[156:159], v[188:191], v[96:99]
	v_mfma_f32_16x16x32_bf16 v[84:87], v[148:151], v[196:199], v[84:87]
	v_mfma_f32_16x16x32_bf16 v[80:83], v[156:159], v[196:199], v[80:83]
	v_mfma_f32_16x16x32_bf16 v[68:71], v[148:151], v[214:217], v[68:71]
	v_mfma_f32_16x16x32_bf16 v[64:67], v[156:159], v[214:217], v[64:67]
	s_barrier
	s_add_i32 s46, s65, s17
	s_mov_b32 m0, s46
	s_add_u32 s98, s50, 0x80
	s_addc_u32 s99, s51, 0
	ds_read_b128 v[160:163], v207 offset:49152
	ds_read_b128 v[164:167], v207 offset:50176
	ds_read_b128 v[184:187], v207 offset:51200
	ds_read_b128 v[188:191], v207 offset:52224
	ds_read_b128 v[192:195], v207 offset:53248
	ds_read_b128 v[196:199], v207 offset:54272
	ds_read_b128 v[210:213], v207 offset:55296
	ds_read_b128 v[214:217], v207 offset:56320
	global_load_lds_dwordx4 v170, s[98:99]
	s_add_i32 m0, s46, 0x2000
	s_add_u32 s46, s50, 0x2b4080
	s_addc_u32 s47, s51, 0
	s_add_i32 s50, s66, s17
	global_load_lds_dwordx4 v174, s[98:99]
	s_mov_b32 m0, s50
	s_nop 0
	global_load_lds_dwordx4 v170, s[46:47]
	s_add_i32 m0, s50, 0x2000
	s_nop 0
	global_load_lds_dwordx4 v174, s[46:47]
	s_add_u32 s100, s52, 0x80
	s_addc_u32 s101, s53, 0
	s_mov_b32 m0, s29
	s_nop 0
	global_load_lds_dwordx4 v168, s[100:101]
	s_mov_b32 m0, s54
	s_nop 0
	global_load_lds_dwordx4 v172, s[100:101]
	s_waitcnt vmcnt(8)
	s_waitcnt lgkmcnt(0)
	s_barrier
	v_mfma_f32_16x16x32_bf16 v[60:63], v[128:131], v[160:163], v[60:63]
	v_mfma_f32_16x16x32_bf16 v[56:59], v[136:139], v[160:163], v[56:59]
	v_mfma_f32_16x16x32_bf16 v[44:47], v[128:131], v[184:187], v[44:47]
	v_mfma_f32_16x16x32_bf16 v[40:43], v[136:139], v[184:187], v[40:43]
	v_mfma_f32_16x16x32_bf16 v[28:31], v[128:131], v[192:195], v[28:31]
	v_mfma_f32_16x16x32_bf16 v[24:27], v[136:139], v[192:195], v[24:27]
	v_mfma_f32_16x16x32_bf16 v[12:15], v[128:131], v[210:213], v[12:15]
	v_mfma_f32_16x16x32_bf16 v[8:11], v[136:139], v[210:213], v[8:11]
	v_mfma_f32_16x16x32_bf16 v[60:63], v[132:135], v[164:167], v[60:63]
	v_mfma_f32_16x16x32_bf16 v[56:59], v[140:143], v[164:167], v[56:59]
	v_mfma_f32_16x16x32_bf16 v[44:47], v[132:135], v[188:191], v[44:47]
	v_mfma_f32_16x16x32_bf16 v[40:43], v[140:143], v[188:191], v[40:43]
	v_mfma_f32_16x16x32_bf16 v[28:31], v[132:135], v[196:199], v[28:31]
	v_mfma_f32_16x16x32_bf16 v[24:27], v[140:143], v[196:199], v[24:27]
	v_mfma_f32_16x16x32_bf16 v[12:15], v[132:135], v[214:217], v[12:15]
	v_mfma_f32_16x16x32_bf16 v[8:11], v[140:143], v[214:217], v[8:11]
	v_mfma_f32_16x16x32_bf16 v[52:55], v[144:147], v[160:163], v[52:55]
	v_mfma_f32_16x16x32_bf16 v[48:51], v[152:155], v[160:163], v[48:51]
	v_mfma_f32_16x16x32_bf16 v[36:39], v[144:147], v[184:187], v[36:39]
	v_mfma_f32_16x16x32_bf16 v[32:35], v[152:155], v[184:187], v[32:35]
	v_mfma_f32_16x16x32_bf16 v[20:23], v[144:147], v[192:195], v[20:23]
	v_mfma_f32_16x16x32_bf16 v[16:19], v[152:155], v[192:195], v[16:19]
	v_mfma_f32_16x16x32_bf16 v[4:7], v[144:147], v[210:213], v[4:7]
	v_mfma_f32_16x16x32_bf16 v[0:3], v[152:155], v[210:213], v[0:3]
	v_mfma_f32_16x16x32_bf16 v[52:55], v[148:151], v[164:167], v[52:55]
	v_mfma_f32_16x16x32_bf16 v[48:51], v[156:159], v[164:167], v[48:51]
	v_mfma_f32_16x16x32_bf16 v[36:39], v[148:151], v[188:191], v[36:39]
	v_mfma_f32_16x16x32_bf16 v[32:35], v[156:159], v[188:191], v[32:35]
	v_mfma_f32_16x16x32_bf16 v[20:23], v[148:151], v[196:199], v[20:23]
	v_mfma_f32_16x16x32_bf16 v[16:19], v[156:159], v[196:199], v[16:19]
	v_mfma_f32_16x16x32_bf16 v[4:7], v[148:151], v[214:217], v[4:7]
	v_mfma_f32_16x16x32_bf16 v[0:3], v[156:159], v[214:217], v[0:3]
	s_barrier
	s_add_i32 s64, s64, 2
	s_add_u32 s62, s62, 0x100
	s_addc_u32 s63, s63, 0
	s_cmpk_gt_u32 s64, 0xa9
	s_mov_b64 s[46:47], s[48:49]
	s_cbranch_scc0 .LBB0_317
	s_and_b64 vcc, exec, s[42:43]
	s_cbranch_vccz .LBB0_320
	s_barrier

; #define PG8_STAGE(bufoff, gbase, voff) do { _Pragma("unroll") for (int _i = 0; _i < 2; ++_i) \
;         __builtin_amdgcn_global_load_lds((const unsigned*)((const char*)(gbase) + (voff)[_i]), (PG8_LAS unsigned*)(lds + (bufoff) + ldsw + _i * 8192), 16, 0, 0); } while (0)
; #define PG8_STAGE_NT(bufoff, gbase, voff) do { _Pragma("unroll") for (int _i = 0; _i < 2; ++_i) \
;         __builtin_amdgcn_global_load_lds((const unsigned*)((const char*)(gbase) + (voff)[_i]), (PG8_LAS unsigned*)(lds + (bufoff) + ldsw + _i * 8192), 16, 0, PG8_B_AUX); } while (0)
; #define PG8_LDA(dst, b, h) do { _Pragma("unroll") for (int m = 0; m < 4; ++m) _Pragma("unroll") for (int k = 0; k < 2; ++k) dst[m][k] = *(const PG8_LAS bf16x8*)(lds + PG8_SA(b, h) + aoff + m * 2048 + k * 1024); } while (0)
; #define PG8_LDB(dst, b, h) do { _Pragma("unroll") for (int n = 0; n < 2; ++n) _Pragma("unroll") for (int k = 0; k < 2; ++k) dst[n][k] = *(const PG8_LAS bf16x8*)(lds + PG8_SB(b, h) + boff + n * 2048 + k * 1024); } while (0)
; #define PG8_WAIT_V(n) asm volatile("s_waitcnt vmcnt(" #n ")" ::: "memory")
; #define PG8_WAIT_L(n) asm volatile("s_waitcnt lgkmcnt(" #n ")" ::: "memory")
; #define PG8_BAR __builtin_amdgcn_s_barrier()
; #define PG8_SCHED __builtin_amdgcn_sched_barrier(0)
; template <class Epi, class Sched, bool ALIGN_EPI = false, bool SP2 = false>
; __device__ __forceinline__ void gemm_phase(PG8_LAS unsigned char* lds, const Gemm g, const Sched& S, const Epi& E, int wid) {
;     ...
;             const bool last = (t == nt - 2);
;             const char* a1 = cA + (size_t)(t + 1) * kstep;
;             const char* a2 = last ? nA : cA + (size_t)(t + 2) * kstep; const char* b2 = last ? nB : cB + (size_t)(t + 2) * kstep;
;             const char* a3 = a2 + kstep; const char* b3 = b2 + kstep;
;             if (last && has_next) S.a_ready(nxt);
;             if constexpr (SP2) {
;             PG8_LDB(B0, 0, 0); PG8_LDB(B1, 0, 1); PG8_SCHED; PG8_LDA(At, 0, 0); PG8_STAGE(PG8_SA(1, 1), a1 + hstepA, voffA);
;             PG8_WAIT_V(8); PG8_WAIT_L(0); PG8_BAR; PG8_MMA(0, 0, At, B0); PG8_MMA(0, 1, At, B1); PG8_BAR; PG8_SCHED;
;             PG8_LDA(At, 0, 1); PG8_STAGE_NT(PG8_SB(0, 0), b2, voffB); PG8_STAGE_NT(PG8_SB(0, 1), b2 + hstepB, voffB); PG8_STAGE(PG8_SA(0, 0), a2, voffA);
;             PG8_WAIT_V(8); PG8_WAIT_L(0); PG8_BAR; PG8_MMA(1, 0, At, B0); PG8_MMA(1, 1, At, B1); PG8_BAR; PG8_SCHED;
.LBB0_426:
	ds_read_b128 v[144:147], v161
	ds_read_b128 v[148:151], v161 offset:1024
	ds_read_b128 v[152:155], v161 offset:2048
	ds_read_b128 v[166:169], v161 offset:3072
	ds_read_b128 v[170:173], v162
	ds_read_b128 v[174:177], v162 offset:1024
	ds_read_b128 v[178:181], v162 offset:2048
	ds_read_b128 v[182:185], v162 offset:3072
	s_add_u32 s4, s46, 0x100
	s_addc_u32 s5, s47, 0
	s_add_u32 s98, s46, 0x80
	s_addc_u32 s99, s47, 0
	s_add_u32 s100, s46, 0x104080
	s_addc_u32 s101, s47, 0
	s_cmp_eq_u32 s64, 60
	s_cselect_b32 s51, s43, s5
	s_cselect_b32 s50, s42, s4
	s_cselect_b32 s49, s45, s63
	s_cselect_b32 s48, s44, s62
	s_add_i32 m0, s23, 0xc000
	ds_read_b128 v[186:189], v163
	ds_read_b128 v[190:193], v163 offset:1024
	ds_read_b128 v[194:197], v163 offset:2048
	ds_read_b128 v[198:201], v163 offset:3072
	ds_read_b128 v[202:205], v163 offset:4096
	ds_read_b128 v[206:209], v163 offset:5120
	ds_read_b128 v[210:213], v163 offset:6144
	ds_read_b128 v[214:217], v163 offset:7168
	global_load_lds_dwordx4 v134, s[100:101]
	s_add_i32 m0, s23, 0xe000
	s_nop 0
	global_load_lds_dwordx4 v130, s[100:101]
	s_waitcnt vmcnt(8)
	s_waitcnt lgkmcnt(0)
	s_barrier
	v_mfma_f32_16x16x32_bf16 v[124:127], v[144:147], v[186:189], v[124:127]
	v_mfma_f32_16x16x32_bf16 v[120:123], v[152:155], v[186:189], v[120:123]
	v_mfma_f32_16x16x32_bf16 v[116:119], v[144:147], v[194:197], v[116:119]
	v_mfma_f32_16x16x32_bf16 v[112:115], v[152:155], v[194:197], v[112:115]
	v_mfma_f32_16x16x32_bf16 v[92:95], v[144:147], v[202:205], v[92:95]
	v_mfma_f32_16x16x32_bf16 v[88:91], v[152:155], v[202:205], v[88:91]
	v_mfma_f32_16x16x32_bf16 v[76:79], v[144:147], v[210:213], v[76:79]
	v_mfma_f32_16x16x32_bf16 v[72:75], v[152:155], v[210:213], v[72:75]
	v_mfma_f32_16x16x32_bf16 v[124:127], v[148:151], v[190:193], v[124:127]
	v_mfma_f32_16x16x32_bf16 v[120:123], v[166:169], v[190:193], v[120:123]
	v_mfma_f32_16x16x32_bf16 v[116:119], v[148:151], v[198:201], v[116:119]
	v_mfma_f32_16x16x32_bf16 v[112:115], v[166:169], v[198:201], v[112:115]
	v_mfma_f32_16x16x32_bf16 v[92:95], v[148:151], v[206:209], v[92:95]
	v_mfma_f32_16x16x32_bf16 v[88:91], v[166:169], v[206:209], v[88:91]
	v_mfma_f32_16x16x32_bf16 v[76:79], v[148:151], v[214:217], v[76:79]
	v_mfma_f32_16x16x32_bf16 v[72:75], v[166:169], v[214:217], v[72:75]
	v_mfma_f32_16x16x32_bf16 v[108:111], v[170:173], v[186:189], v[108:111]
	v_mfma_f32_16x16x32_bf16 v[104:107], v[178:181], v[186:189], v[104:107]
	v_mfma_f32_16x16x32_bf16 v[100:103], v[170:173], v[194:197], v[100:103]
	v_mfma_f32_16x16x32_bf16 v[96:99], v[178:181], v[194:197], v[96:99]
	v_mfma_f32_16x16x32_bf16 v[84:87], v[170:173], v[202:205], v[84:87]
	v_mfma_f32_16x16x32_bf16 v[80:83], v[178:181], v[202:205], v[80:83]
	v_mfma_f32_16x16x32_bf16 v[68:71], v[170:173], v[210:213], v[68:71]
	v_mfma_f32_16x16x32_bf16 v[64:67], v[178:181], v[210:213], v[64:67]
	v_mfma_f32_16x16x32_bf16 v[108:111], v[174:177], v[190:193], v[108:111]
	v_mfma_f32_16x16x32_bf16 v[104:107], v[182:185], v[190:193], v[104:107]
	v_mfma_f32_16x16x32_bf16 v[100:103], v[174:177], v[198:201], v[100:103]
	v_mfma_f32_16x16x32_bf16 v[96:99], v[182:185], v[198:201], v[96:99]
	v_mfma_f32_16x16x32_bf16 v[84:87], v[174:177], v[206:209], v[84:87]
	v_mfma_f32_16x16x32_bf16 v[80:83], v[182:185], v[206:209], v[80:83]
	v_mfma_f32_16x16x32_bf16 v[68:71], v[174:177], v[214:217], v[68:71]
	v_mfma_f32_16x16x32_bf16 v[64:67], v[182:185], v[214:217], v[64:67]
	s_barrier
	s_add_i32 s46, s56, s17
	s_mov_b32 m0, s46
	ds_read_b128 v[186:189], v163 offset:16384
	ds_read_b128 v[190:193], v163 offset:17408
	ds_read_b128 v[194:197], v163 offset:18432
	ds_read_b128 v[198:201], v163 offset:19456
	ds_read_b128 v[202:205], v163 offset:20480
	ds_read_b128 v[206:209], v163 offset:21504
	ds_read_b128 v[210:213], v163 offset:22528
	ds_read_b128 v[214:217], v163 offset:23552
	global_load_lds_dwordx4 v132, s[48:49]
	s_add_i32 m0, s46, 0x2000
	s_add_u32 s46, s48, 0x104000
	s_addc_u32 s47, s49, 0
	s_add_i32 s65, s57, s17
	global_load_lds_dwordx4 v128, s[48:49]
	s_mov_b32 m0, s65
	s_nop 0
	global_load_lds_dwordx4 v132, s[46:47]
	s_add_i32 m0, s65, 0x2000
	s_nop 0
	global_load_lds_dwordx4 v128, s[46:47]
	s_mov_b32 m0, s23
	s_nop 0
	global_load_lds_dwordx4 v134, s[50:51]
	s_mov_b32 m0, s24
	s_nop 0
	global_load_lds_dwordx4 v130, s[50:51]
	s_waitcnt vmcnt(8)
	s_waitcnt lgkmcnt(0)
	s_barrier
	v_mfma_f32_16x16x32_bf16 v[60:63], v[144:147], v[186:189], v[60:63]
	v_mfma_f32_16x16x32_bf16 v[56:59], v[152:155], v[186:189], v[56:59]
	v_mfma_f32_16x16x32_bf16 v[44:47], v[144:147], v[194:197], v[44:47]
	v_mfma_f32_16x16x32_bf16 v[40:43], v[152:155], v[194:197], v[40:43]
	v_mfma_f32_16x16x32_bf16 v[28:31], v[144:147], v[202:205], v[28:31]
	v_mfma_f32_16x16x32_bf16 v[24:27], v[152:155], v[202:205], v[24:27]
	v_mfma_f32_16x16x32_bf16 v[12:15], v[144:147], v[210:213], v[12:15]
	v_mfma_f32_16x16x32_bf16 v[8:11], v[152:155], v[210:213], v[8:11]
	v_mfma_f32_16x16x32_bf16 v[60:63], v[148:151], v[190:193], v[60:63]
	v_mfma_f32_16x16x32_bf16 v[56:59], v[166:169], v[190:193], v[56:59]
	v_mfma_f32_16x16x32_bf16 v[44:47], v[148:151], v[198:201], v[44:47]
	v_mfma_f32_16x16x32_bf16 v[40:43], v[166:169], v[198:201], v[40:43]
	v_mfma_f32_16x16x32_bf16 v[28:31], v[148:151], v[206:209], v[28:31]
	v_mfma_f32_16x16x32_bf16 v[24:27], v[166:169], v[206:209], v[24:27]
	v_mfma_f32_16x16x32_bf16 v[12:15], v[148:151], v[214:217], v[12:15]
	v_mfma_f32_16x16x32_bf16 v[8:11], v[166:169], v[214:217], v[8:11]
	v_mfma_f32_16x16x32_bf16 v[52:55], v[170:173], v[186:189], v[52:55]
	v_mfma_f32_16x16x32_bf16 v[48:51], v[178:181], v[186:189], v[48:51]
	v_mfma_f32_16x16x32_bf16 v[36:39], v[170:173], v[194:197], v[36:39]
	v_mfma_f32_16x16x32_bf16 v[32:35], v[178:181], v[194:197], v[32:35]
	v_mfma_f32_16x16x32_bf16 v[20:23], v[170:173], v[202:205], v[20:23]
	v_mfma_f32_16x16x32_bf16 v[16:19], v[178:181], v[202:205], v[16:19]
	v_mfma_f32_16x16x32_bf16 v[4:7], v[170:173], v[210:213], v[4:7]
	v_mfma_f32_16x16x32_bf16 v[0:3], v[178:181], v[210:213], v[0:3]
	v_mfma_f32_16x16x32_bf16 v[52:55], v[174:177], v[190:193], v[52:55]
	v_mfma_f32_16x16x32_bf16 v[48:51], v[182:185], v[190:193], v[48:51]
	v_mfma_f32_16x16x32_bf16 v[36:39], v[174:177], v[198:201], v[36:39]
	v_mfma_f32_16x16x32_bf16 v[32:35], v[182:185], v[198:201], v[32:35]
	v_mfma_f32_16x16x32_bf16 v[20:23], v[174:177], v[206:209], v[20:23]
	v_mfma_f32_16x16x32_bf16 v[16:19], v[182:185], v[206:209], v[16:19]
	v_mfma_f32_16x16x32_bf16 v[4:7], v[174:177], v[214:217], v[4:7]
	v_mfma_f32_16x16x32_bf16 v[0:3], v[182:185], v[214:217], v[0:3]
	s_barrier
; #define PG8_STAGE(bufoff, gbase, voff) do { _Pragma("unroll") for (int _i = 0; _i < 2; ++_i) \
;         __builtin_amdgcn_global_load_lds((const unsigned*)((const char*)(gbase) + (voff)[_i]), (PG8_LAS unsigned*)(lds + (bufoff) + ldsw + _i * 8192), 16, 0, 0); } while (0)
; #define PG8_STAGE_NT(bufoff, gbase, voff) do { _Pragma("unroll") for (int _i = 0; _i < 2; ++_i) \
;         __builtin_amdgcn_global_load_lds((const unsigned*)((const char*)(gbase) + (voff)[_i]), (PG8_LAS unsigned*)(lds + (bufoff) + ldsw + _i * 8192), 16, 0, PG8_B_AUX); } while (0)
; #define PG8_LDA(dst, b, h) do { _Pragma("unroll") for (int m = 0; m < 4; ++m) _Pragma("unroll") for (int k = 0; k < 2; ++k) dst[m][k] = *(const PG8_LAS bf16x8*)(lds + PG8_SA(b, h) + aoff + m * 2048 + k * 1024); } while (0)
; #define PG8_LDB(dst, b, h) do { _Pragma("unroll") for (int n = 0; n < 2; ++n) _Pragma("unroll") for (int k = 0; k < 2; ++k) dst[n][k] = *(const PG8_LAS bf16x8*)(lds + PG8_SB(b, h) + boff + n * 2048 + k * 1024); } while (0)
; #define PG8_MMA(ai, bj, At, Bt) do { __builtin_amdgcn_s_setprio(1); _Pragma("unroll") for (int m = 0; m < 4; ++m) _Pragma("unroll") for (int n = 0; n < 2; ++n) _Pragma("unroll") for (int k = 0; k < 2; ++k) \
;         acc[ai][bj][m][n] = __builtin_amdgcn_mfma_f32_16x16x32_bf16(Bt[n][k], At[m][k], acc[ai][bj][m][n], 0, 0, 0); __builtin_amdgcn_s_setprio(0); } while (0)
; #define PG8_WAIT_V(n) asm volatile("s_waitcnt vmcnt(" #n ")" ::: "memory")
; #define PG8_WAIT_L(n) asm volatile("s_waitcnt lgkmcnt(" #n ")" ::: "memory")
; #define PG8_BAR __builtin_amdgcn_s_barrier()
; #define PG8_SCHED __builtin_amdgcn_sched_barrier(0)
; template <class Epi, class Sched, bool ALIGN_EPI = false, bool SP2 = false>
; __device__ __forceinline__ void gemm_phase(PG8_LAS unsigned char* lds, const Gemm g, const Sched& S, const Epi& E, int wid) {
;     ...
;             PG8_LDB(B0, 1, 0); PG8_LDB(B1, 1, 1); PG8_SCHED; PG8_LDA(At, 1, 0); PG8_STAGE(PG8_SA(0, 1), a2 + hstepA, voffA);
;             PG8_WAIT_V(8); PG8_WAIT_L(0); PG8_BAR; PG8_MMA(0, 0, At, B0); PG8_MMA(0, 1, At, B1); PG8_BAR; PG8_SCHED;
;             PG8_LDA(At, 1, 1); PG8_STAGE_NT(PG8_SB(1, 0), b3, voffB); PG8_STAGE_NT(PG8_SB(1, 1), b3 + hstepB, voffB); PG8_STAGE(PG8_SA(1, 0), a3, voffA);
;             PG8_WAIT_V(8); PG8_WAIT_L(0); PG8_BAR; PG8_MMA(1, 0, At, B0); PG8_MMA(1, 1, At, B1); PG8_BAR; PG8_SCHED;
	s_add_i32 s65, 0, 0x18000
	v_add_u32_e32 v165, s65, v159
	s_add_i32 s66, 0, 0x1c000
	ds_read_b128 v[144:147], v165
	ds_read_b128 v[148:151], v165 offset:1024
	ds_read_b128 v[152:155], v165 offset:2048
	ds_read_b128 v[166:169], v165 offset:3072
	v_add_u32_e32 v165, s66, v159
	ds_read_b128 v[170:173], v165
	ds_read_b128 v[174:177], v165 offset:1024
	ds_read_b128 v[178:181], v165 offset:2048
	ds_read_b128 v[182:185], v165 offset:3072
	s_add_u32 s46, s50, 0x104000
	s_addc_u32 s47, s51, 0
	s_mov_b32 m0, s25
	ds_read_b128 v[186:189], v163 offset:32768
	ds_read_b128 v[190:193], v163 offset:33792
	ds_read_b128 v[194:197], v163 offset:34816
	ds_read_b128 v[198:201], v163 offset:35840
	ds_read_b128 v[202:205], v163 offset:36864
	ds_read_b128 v[206:209], v163 offset:37888
	ds_read_b128 v[210:213], v163 offset:38912
	ds_read_b128 v[214:217], v163 offset:39936
	global_load_lds_dwordx4 v134, s[46:47]
	s_mov_b32 m0, s29
	s_nop 0
	global_load_lds_dwordx4 v130, s[46:47]
	s_waitcnt vmcnt(8)
	s_waitcnt lgkmcnt(0)
	s_barrier
	v_mfma_f32_16x16x32_bf16 v[124:127], v[144:147], v[186:189], v[124:127]
	v_mfma_f32_16x16x32_bf16 v[120:123], v[152:155], v[186:189], v[120:123]
	v_mfma_f32_16x16x32_bf16 v[116:119], v[144:147], v[194:197], v[116:119]
	v_mfma_f32_16x16x32_bf16 v[112:115], v[152:155], v[194:197], v[112:115]
	v_mfma_f32_16x16x32_bf16 v[92:95], v[144:147], v[202:205], v[92:95]
	v_mfma_f32_16x16x32_bf16 v[88:91], v[152:155], v[202:205], v[88:91]
	v_mfma_f32_16x16x32_bf16 v[76:79], v[144:147], v[210:213], v[76:79]
	v_mfma_f32_16x16x32_bf16 v[72:75], v[152:155], v[210:213], v[72:75]
	v_mfma_f32_16x16x32_bf16 v[124:127], v[148:151], v[190:193], v[124:127]
	v_mfma_f32_16x16x32_bf16 v[120:123], v[166:169], v[190:193], v[120:123]
	v_mfma_f32_16x16x32_bf16 v[116:119], v[148:151], v[198:201], v[116:119]
	v_mfma_f32_16x16x32_bf16 v[112:115], v[166:169], v[198:201], v[112:115]
	v_mfma_f32_16x16x32_bf16 v[92:95], v[148:151], v[206:209], v[92:95]
	v_mfma_f32_16x16x32_bf16 v[88:91], v[166:169], v[206:209], v[88:91]
	v_mfma_f32_16x16x32_bf16 v[76:79], v[148:151], v[214:217], v[76:79]
	v_mfma_f32_16x16x32_bf16 v[72:75], v[166:169], v[214:217], v[72:75]
	v_mfma_f32_16x16x32_bf16 v[108:111], v[170:173], v[186:189], v[108:111]
	v_mfma_f32_16x16x32_bf16 v[104:107], v[178:181], v[186:189], v[104:107]
	v_mfma_f32_16x16x32_bf16 v[100:103], v[170:173], v[194:197], v[100:103]
	v_mfma_f32_16x16x32_bf16 v[96:99], v[178:181], v[194:197], v[96:99]
	v_mfma_f32_16x16x32_bf16 v[84:87], v[170:173], v[202:205], v[84:87]
	v_mfma_f32_16x16x32_bf16 v[80:83], v[178:181], v[202:205], v[80:83]
	v_mfma_f32_16x16x32_bf16 v[68:71], v[170:173], v[210:213], v[68:71]
	v_mfma_f32_16x16x32_bf16 v[64:67], v[178:181], v[210:213], v[64:67]
	v_mfma_f32_16x16x32_bf16 v[108:111], v[174:177], v[190:193], v[108:111]
	v_mfma_f32_16x16x32_bf16 v[104:107], v[182:185], v[190:193], v[104:107]
	v_mfma_f32_16x16x32_bf16 v[100:103], v[174:177], v[198:201], v[100:103]
	v_mfma_f32_16x16x32_bf16 v[96:99], v[182:185], v[198:201], v[96:99]
	v_mfma_f32_16x16x32_bf16 v[84:87], v[174:177], v[206:209], v[84:87]
	v_mfma_f32_16x16x32_bf16 v[80:83], v[182:185], v[206:209], v[80:83]
	v_mfma_f32_16x16x32_bf16 v[68:71], v[174:177], v[214:217], v[68:71]
	v_mfma_f32_16x16x32_bf16 v[64:67], v[182:185], v[214:217], v[64:67]
	s_barrier
	s_add_i32 s46, s65, s17
	s_mov_b32 m0, s46
	s_add_u32 s98, s48, 0x80
	s_addc_u32 s99, s49, 0
	ds_read_b128 v[186:189], v163 offset:49152
	ds_read_b128 v[190:193], v163 offset:50176
	ds_read_b128 v[194:197], v163 offset:51200
	ds_read_b128 v[198:201], v163 offset:52224
	ds_read_b128 v[202:205], v163 offset:53248
	ds_read_b128 v[206:209], v163 offset:54272
	ds_read_b128 v[210:213], v163 offset:55296
	ds_read_b128 v[214:217], v163 offset:56320
	global_load_lds_dwordx4 v132, s[98:99]
	s_add_i32 m0, s46, 0x2000
	s_add_u32 s46, s48, 0x104080
	s_addc_u32 s47, s49, 0
	s_add_i32 s48, s66, s17
	global_load_lds_dwordx4 v128, s[98:99]
	s_mov_b32 m0, s48
	s_nop 0
	global_load_lds_dwordx4 v132, s[46:47]
	s_add_i32 m0, s48, 0x2000
	s_nop 0
	global_load_lds_dwordx4 v128, s[46:47]
	s_add_u32 s100, s50, 0x80
	s_addc_u32 s101, s51, 0
	s_mov_b32 m0, s53
	s_nop 0
	global_load_lds_dwordx4 v134, s[100:101]
	s_mov_b32 m0, s54
	s_nop 0
	global_load_lds_dwordx4 v130, s[100:101]
	s_waitcnt vmcnt(8)
	s_waitcnt lgkmcnt(0)
	s_barrier
	v_mfma_f32_16x16x32_bf16 v[60:63], v[144:147], v[186:189], v[60:63]
	v_mfma_f32_16x16x32_bf16 v[56:59], v[152:155], v[186:189], v[56:59]
	v_mfma_f32_16x16x32_bf16 v[44:47], v[144:147], v[194:197], v[44:47]
	v_mfma_f32_16x16x32_bf16 v[40:43], v[152:155], v[194:197], v[40:43]
	v_mfma_f32_16x16x32_bf16 v[28:31], v[144:147], v[202:205], v[28:31]
	v_mfma_f32_16x16x32_bf16 v[24:27], v[152:155], v[202:205], v[24:27]
	v_mfma_f32_16x16x32_bf16 v[12:15], v[144:147], v[210:213], v[12:15]
	v_mfma_f32_16x16x32_bf16 v[8:11], v[152:155], v[210:213], v[8:11]
	v_mfma_f32_16x16x32_bf16 v[60:63], v[148:151], v[190:193], v[60:63]
	v_mfma_f32_16x16x32_bf16 v[56:59], v[166:169], v[190:193], v[56:59]
	v_mfma_f32_16x16x32_bf16 v[44:47], v[148:151], v[198:201], v[44:47]
	v_mfma_f32_16x16x32_bf16 v[40:43], v[166:169], v[198:201], v[40:43]
	v_mfma_f32_16x16x32_bf16 v[28:31], v[148:151], v[206:209], v[28:31]
	v_mfma_f32_16x16x32_bf16 v[24:27], v[166:169], v[206:209], v[24:27]
	v_mfma_f32_16x16x32_bf16 v[12:15], v[148:151], v[214:217], v[12:15]
	v_mfma_f32_16x16x32_bf16 v[8:11], v[166:169], v[214:217], v[8:11]
	v_mfma_f32_16x16x32_bf16 v[52:55], v[170:173], v[186:189], v[52:55]
	v_mfma_f32_16x16x32_bf16 v[48:51], v[178:181], v[186:189], v[48:51]
	v_mfma_f32_16x16x32_bf16 v[36:39], v[170:173], v[194:197], v[36:39]
	v_mfma_f32_16x16x32_bf16 v[32:35], v[178:181], v[194:197], v[32:35]
	v_mfma_f32_16x16x32_bf16 v[20:23], v[170:173], v[202:205], v[20:23]
	v_mfma_f32_16x16x32_bf16 v[16:19], v[178:181], v[202:205], v[16:19]
	v_mfma_f32_16x16x32_bf16 v[4:7], v[170:173], v[210:213], v[4:7]
	v_mfma_f32_16x16x32_bf16 v[0:3], v[178:181], v[210:213], v[0:3]
	v_mfma_f32_16x16x32_bf16 v[52:55], v[174:177], v[190:193], v[52:55]
	v_mfma_f32_16x16x32_bf16 v[48:51], v[182:185], v[190:193], v[48:51]
	v_mfma_f32_16x16x32_bf16 v[36:39], v[174:177], v[198:201], v[36:39]
	v_mfma_f32_16x16x32_bf16 v[32:35], v[182:185], v[198:201], v[32:35]
	v_mfma_f32_16x16x32_bf16 v[20:23], v[174:177], v[206:209], v[20:23]
	v_mfma_f32_16x16x32_bf16 v[16:19], v[182:185], v[206:209], v[16:19]
	v_mfma_f32_16x16x32_bf16 v[4:7], v[174:177], v[214:217], v[4:7]
	v_mfma_f32_16x16x32_bf16 v[0:3], v[182:185], v[214:217], v[0:3]
	s_barrier
	s_add_i32 s64, s64, 2
	s_add_u32 s62, s62, 0x100
	s_addc_u32 s63, s63, 0
	s_cmp_gt_u32 s64, 61
	s_mov_b64 s[46:47], s[4:5]
	s_cbranch_scc0 .LBB0_426
	s_and_b64 vcc, exec, s[40:41]
	s_cbranch_vccz .LBB0_429
	s_barrier

; #define PG8_STAGE(bufoff, gbase, voff) do { _Pragma("unroll") for (int _i = 0; _i < 2; ++_i) \
;         __builtin_amdgcn_global_load_lds((const unsigned*)((const char*)(gbase) + (voff)[_i]), (PG8_LAS unsigned*)(lds + (bufoff) + ldsw + _i * 8192), 16, 0, 0); } while (0)
; #define PG8_STAGE_NT(bufoff, gbase, voff) do { _Pragma("unroll") for (int _i = 0; _i < 2; ++_i) \
;         __builtin_amdgcn_global_load_lds((const unsigned*)((const char*)(gbase) + (voff)[_i]), (PG8_LAS unsigned*)(lds + (bufoff) + ldsw + _i * 8192), 16, 0, PG8_B_AUX); } while (0)
; #define PG8_LDA(dst, b, h) do { _Pragma("unroll") for (int m = 0; m < 4; ++m) _Pragma("unroll") for (int k = 0; k < 2; ++k) dst[m][k] = *(const PG8_LAS bf16x8*)(lds + PG8_SA(b, h) + aoff + m * 2048 + k * 1024); } while (0)
; #define PG8_LDB(dst, b, h) do { _Pragma("unroll") for (int n = 0; n < 2; ++n) _Pragma("unroll") for (int k = 0; k < 2; ++k) dst[n][k] = *(const PG8_LAS bf16x8*)(lds + PG8_SB(b, h) + boff + n * 2048 + k * 1024); } while (0)
; #define PG8_MMA(ai, bj, At, Bt) do { __builtin_amdgcn_s_setprio(1); _Pragma("unroll") for (int m = 0; m < 4; ++m) _Pragma("unroll") for (int n = 0; n < 2; ++n) _Pragma("unroll") for (int k = 0; k < 2; ++k) \
;         acc[ai][bj][m][n] = __builtin_amdgcn_mfma_f32_16x16x32_bf16(Bt[n][k], At[m][k], acc[ai][bj][m][n], 0, 0, 0); __builtin_amdgcn_s_setprio(0); } while (0)
; #define PG8_WAIT_V(n) asm volatile("s_waitcnt vmcnt(" #n ")" ::: "memory")
; #define PG8_WAIT_L(n) asm volatile("s_waitcnt lgkmcnt(" #n ")" ::: "memory")
; #define PG8_BAR __builtin_amdgcn_s_barrier()
; #define PG8_SCHED __builtin_amdgcn_sched_barrier(0)
; template <class Epi, class Sched, bool ALIGN_EPI = false, bool SP2 = false>
; __device__ __forceinline__ void gemm_phase(PG8_LAS unsigned char* lds, const Gemm g, const Sched& S, const Epi& E, int wid) {
;     ...
;             PG8_LDB(B0, 0, 0); PG8_LDB(B1, 0, 1); PG8_SCHED; PG8_LDA(At, 0, 0); PG8_STAGE(PG8_SA(1, 1), a1 + hstepA, voffA);
;             PG8_WAIT_V(8); PG8_WAIT_L(0); PG8_BAR; PG8_MMA(0, 0, At, B0); PG8_MMA(0, 1, At, B1); PG8_BAR; PG8_SCHED;
;             PG8_LDA(At, 0, 1); PG8_STAGE_NT(PG8_SB(0, 0), b2, voffB); PG8_STAGE_NT(PG8_SB(0, 1), b2 + hstepB, voffB); PG8_STAGE(PG8_SA(0, 0), a2, voffA);
;             PG8_WAIT_V(8); PG8_WAIT_L(0); PG8_BAR; PG8_MMA(1, 0, At, B0); PG8_MMA(1, 1, At, B1); PG8_BAR; PG8_SCHED;
.LBB0_1037:
	ds_read_b128 v[104:107], v221
	ds_read_b128 v[116:119], v221 offset:1024
	ds_read_b128 v[128:131], v221 offset:2048
	ds_read_b128 v[140:143], v221 offset:3072
	ds_read_b128 v[144:147], v222
	ds_read_b128 v[148:151], v222 offset:1024
	ds_read_b128 v[152:155], v222 offset:2048
	ds_read_b128 v[156:159], v222 offset:3072
	s_add_u32 s52, s50, 0x100
	s_addc_u32 s53, s51, 0
	s_add_u32 s98, s50, 0x80
	s_addc_u32 s99, s51, 0
	s_add_u32 s100, s50, 0x104080
	s_addc_u32 s101, s51, 0
	s_cmp_eq_u32 s67, 60
	s_cselect_b32 s57, s7, s53
	s_cselect_b32 s56, s6, s52
	s_cselect_b32 s55, s49, s66
	s_cselect_b32 s54, s48, s65
	s_add_i32 m0, s17, 0xc000
	ds_read_b128 v[160:163], v223
	ds_read_b128 v[164:167], v223 offset:1024
	ds_read_b128 v[168:171], v223 offset:2048
	ds_read_b128 v[172:175], v223 offset:3072
	ds_read_b128 v[176:179], v223 offset:4096
	ds_read_b128 v[180:183], v223 offset:5120
	ds_read_b128 v[200:203], v223 offset:6144
	ds_read_b128 v[204:207], v223 offset:7168
	global_load_lds_dwordx4 v184, s[100:101]
	s_add_i32 m0, s17, 0xe000
	s_nop 0
	global_load_lds_dwordx4 v188, s[100:101]
	s_waitcnt vmcnt(8)
	s_waitcnt lgkmcnt(0)
	s_barrier
	v_mfma_f32_16x16x32_bf16 v[136:139], v[104:107], v[160:163], v[136:139]
	v_mfma_f32_16x16x32_bf16 v[132:135], v[128:131], v[160:163], v[132:135]
	v_mfma_f32_16x16x32_bf16 v[112:115], v[104:107], v[168:171], v[112:115]
	v_mfma_f32_16x16x32_bf16 v[108:111], v[128:131], v[168:171], v[108:111]
	v_mfma_f32_16x16x32_bf16 v[92:95], v[104:107], v[176:179], v[92:95]
	v_mfma_f32_16x16x32_bf16 v[88:91], v[128:131], v[176:179], v[88:91]
	v_mfma_f32_16x16x32_bf16 v[76:79], v[104:107], v[200:203], v[76:79]
	v_mfma_f32_16x16x32_bf16 v[72:75], v[128:131], v[200:203], v[72:75]
	v_mfma_f32_16x16x32_bf16 v[136:139], v[116:119], v[164:167], v[136:139]
	v_mfma_f32_16x16x32_bf16 v[132:135], v[140:143], v[164:167], v[132:135]
	v_mfma_f32_16x16x32_bf16 v[112:115], v[116:119], v[172:175], v[112:115]
	v_mfma_f32_16x16x32_bf16 v[108:111], v[140:143], v[172:175], v[108:111]
	v_mfma_f32_16x16x32_bf16 v[92:95], v[116:119], v[180:183], v[92:95]
	v_mfma_f32_16x16x32_bf16 v[88:91], v[140:143], v[180:183], v[88:91]
	v_mfma_f32_16x16x32_bf16 v[76:79], v[116:119], v[204:207], v[76:79]
	v_mfma_f32_16x16x32_bf16 v[72:75], v[140:143], v[204:207], v[72:75]
	v_mfma_f32_16x16x32_bf16 v[124:127], v[144:147], v[160:163], v[124:127]
	v_mfma_f32_16x16x32_bf16 v[120:123], v[152:155], v[160:163], v[120:123]
	v_mfma_f32_16x16x32_bf16 v[100:103], v[144:147], v[168:171], v[100:103]
	v_mfma_f32_16x16x32_bf16 v[96:99], v[152:155], v[168:171], v[96:99]
	v_mfma_f32_16x16x32_bf16 v[84:87], v[144:147], v[176:179], v[84:87]
	v_mfma_f32_16x16x32_bf16 v[80:83], v[152:155], v[176:179], v[80:83]
	v_mfma_f32_16x16x32_bf16 v[68:71], v[144:147], v[200:203], v[68:71]
	v_mfma_f32_16x16x32_bf16 v[64:67], v[152:155], v[200:203], v[64:67]
	v_mfma_f32_16x16x32_bf16 v[124:127], v[148:151], v[164:167], v[124:127]
	v_mfma_f32_16x16x32_bf16 v[120:123], v[156:159], v[164:167], v[120:123]
	v_mfma_f32_16x16x32_bf16 v[100:103], v[148:151], v[172:175], v[100:103]
	v_mfma_f32_16x16x32_bf16 v[96:99], v[156:159], v[172:175], v[96:99]
	v_mfma_f32_16x16x32_bf16 v[84:87], v[148:151], v[180:183], v[84:87]
	v_mfma_f32_16x16x32_bf16 v[80:83], v[156:159], v[180:183], v[80:83]
	v_mfma_f32_16x16x32_bf16 v[68:71], v[148:151], v[204:207], v[68:71]
	v_mfma_f32_16x16x32_bf16 v[64:67], v[156:159], v[204:207], v[64:67]
	s_barrier
	s_add_i32 s50, s60, s9
	s_mov_b32 m0, s50
	ds_read_b128 v[160:163], v223 offset:16384
	ds_read_b128 v[164:167], v223 offset:17408
	ds_read_b128 v[168:171], v223 offset:18432
	ds_read_b128 v[172:175], v223 offset:19456
	ds_read_b128 v[176:179], v223 offset:20480
	ds_read_b128 v[180:183], v223 offset:21504
	ds_read_b128 v[200:203], v223 offset:22528
	ds_read_b128 v[204:207], v223 offset:23552
	global_load_lds_dwordx4 v186, s[54:55]
	s_add_i32 m0, s50, 0x2000
	s_add_u32 s50, s54, 0x104000
	s_addc_u32 s51, s55, 0
	s_add_i32 s68, s61, s9
	global_load_lds_dwordx4 v190, s[54:55]
	s_mov_b32 m0, s68
	s_nop 0
	global_load_lds_dwordx4 v186, s[50:51]
	s_add_i32 m0, s68, 0x2000
	s_nop 0
	global_load_lds_dwordx4 v190, s[50:51]
	s_mov_b32 m0, s17
	s_nop 0
	global_load_lds_dwordx4 v184, s[56:57]
	s_mov_b32 m0, s19
	s_nop 0
	global_load_lds_dwordx4 v188, s[56:57]
	s_waitcnt vmcnt(8)
	s_waitcnt lgkmcnt(0)
	s_barrier
	v_mfma_f32_16x16x32_bf16 v[60:63], v[104:107], v[160:163], v[60:63]
	v_mfma_f32_16x16x32_bf16 v[56:59], v[128:131], v[160:163], v[56:59]
	v_mfma_f32_16x16x32_bf16 v[44:47], v[104:107], v[168:171], v[44:47]
	v_mfma_f32_16x16x32_bf16 v[40:43], v[128:131], v[168:171], v[40:43]
	v_mfma_f32_16x16x32_bf16 v[28:31], v[104:107], v[176:179], v[28:31]
	v_mfma_f32_16x16x32_bf16 v[24:27], v[128:131], v[176:179], v[24:27]
	v_mfma_f32_16x16x32_bf16 v[12:15], v[104:107], v[200:203], v[12:15]
	v_mfma_f32_16x16x32_bf16 v[8:11], v[128:131], v[200:203], v[8:11]
	v_mfma_f32_16x16x32_bf16 v[60:63], v[116:119], v[164:167], v[60:63]
	v_mfma_f32_16x16x32_bf16 v[56:59], v[140:143], v[164:167], v[56:59]
	v_mfma_f32_16x16x32_bf16 v[44:47], v[116:119], v[172:175], v[44:47]
	v_mfma_f32_16x16x32_bf16 v[40:43], v[140:143], v[172:175], v[40:43]
	v_mfma_f32_16x16x32_bf16 v[28:31], v[116:119], v[180:183], v[28:31]
	v_mfma_f32_16x16x32_bf16 v[24:27], v[140:143], v[180:183], v[24:27]
	v_mfma_f32_16x16x32_bf16 v[12:15], v[116:119], v[204:207], v[12:15]
	v_mfma_f32_16x16x32_bf16 v[8:11], v[140:143], v[204:207], v[8:11]
	v_mfma_f32_16x16x32_bf16 v[52:55], v[144:147], v[160:163], v[52:55]
	v_mfma_f32_16x16x32_bf16 v[48:51], v[152:155], v[160:163], v[48:51]
	v_mfma_f32_16x16x32_bf16 v[36:39], v[144:147], v[168:171], v[36:39]
	v_mfma_f32_16x16x32_bf16 v[32:35], v[152:155], v[168:171], v[32:35]
	v_mfma_f32_16x16x32_bf16 v[20:23], v[144:147], v[176:179], v[20:23]
	v_mfma_f32_16x16x32_bf16 v[16:19], v[152:155], v[176:179], v[16:19]
	v_mfma_f32_16x16x32_bf16 v[4:7], v[144:147], v[200:203], v[4:7]
	v_mfma_f32_16x16x32_bf16 v[0:3], v[152:155], v[200:203], v[0:3]
	v_mfma_f32_16x16x32_bf16 v[52:55], v[148:151], v[164:167], v[52:55]
	v_mfma_f32_16x16x32_bf16 v[48:51], v[156:159], v[164:167], v[48:51]
	v_mfma_f32_16x16x32_bf16 v[36:39], v[148:151], v[172:175], v[36:39]
	v_mfma_f32_16x16x32_bf16 v[32:35], v[156:159], v[172:175], v[32:35]
	v_mfma_f32_16x16x32_bf16 v[20:23], v[148:151], v[180:183], v[20:23]
	v_mfma_f32_16x16x32_bf16 v[16:19], v[156:159], v[180:183], v[16:19]
	v_mfma_f32_16x16x32_bf16 v[4:7], v[148:151], v[204:207], v[4:7]
	v_mfma_f32_16x16x32_bf16 v[0:3], v[156:159], v[204:207], v[0:3]
	s_barrier
; #define PG8_STAGE(bufoff, gbase, voff) do { _Pragma("unroll") for (int _i = 0; _i < 2; ++_i) \
;         __builtin_amdgcn_global_load_lds((const unsigned*)((const char*)(gbase) + (voff)[_i]), (PG8_LAS unsigned*)(lds + (bufoff) + ldsw + _i * 8192), 16, 0, 0); } while (0)
; #define PG8_STAGE_NT(bufoff, gbase, voff) do { _Pragma("unroll") for (int _i = 0; _i < 2; ++_i) \
;         __builtin_amdgcn_global_load_lds((const unsigned*)((const char*)(gbase) + (voff)[_i]), (PG8_LAS unsigned*)(lds + (bufoff) + ldsw + _i * 8192), 16, 0, PG8_B_AUX); } while (0)
; #define PG8_LDA(dst, b, h) do { _Pragma("unroll") for (int m = 0; m < 4; ++m) _Pragma("unroll") for (int k = 0; k < 2; ++k) dst[m][k] = *(const PG8_LAS bf16x8*)(lds + PG8_SA(b, h) + aoff + m * 2048 + k * 1024); } while (0)
; #define PG8_LDB(dst, b, h) do { _Pragma("unroll") for (int n = 0; n < 2; ++n) _Pragma("unroll") for (int k = 0; k < 2; ++k) dst[n][k] = *(const PG8_LAS bf16x8*)(lds + PG8_SB(b, h) + boff + n * 2048 + k * 1024); } while (0)
; #define PG8_MMA(ai, bj, At, Bt) do { __builtin_amdgcn_s_setprio(1); _Pragma("unroll") for (int m = 0; m < 4; ++m) _Pragma("unroll") for (int n = 0; n < 2; ++n) _Pragma("unroll") for (int k = 0; k < 2; ++k) \
;         acc[ai][bj][m][n] = __builtin_amdgcn_mfma_f32_16x16x32_bf16(Bt[n][k], At[m][k], acc[ai][bj][m][n], 0, 0, 0); __builtin_amdgcn_s_setprio(0); } while (0)
; #define PG8_WAIT_V(n) asm volatile("s_waitcnt vmcnt(" #n ")" ::: "memory")
; #define PG8_WAIT_L(n) asm volatile("s_waitcnt lgkmcnt(" #n ")" ::: "memory")
; #define PG8_BAR __builtin_amdgcn_s_barrier()
; #define PG8_SCHED __builtin_amdgcn_sched_barrier(0)
; template <class Epi, class Sched, bool ALIGN_EPI = false, bool SP2 = false>
; __device__ __forceinline__ void gemm_phase(PG8_LAS unsigned char* lds, const Gemm g, const Sched& S, const Epi& E, int wid) {
;     ...
;             PG8_LDB(B0, 1, 0); PG8_LDB(B1, 1, 1); PG8_SCHED; PG8_LDA(At, 1, 0); PG8_STAGE(PG8_SA(0, 1), a2 + hstepA, voffA);
;             PG8_WAIT_V(8); PG8_WAIT_L(0); PG8_BAR; PG8_MMA(0, 0, At, B0); PG8_MMA(0, 1, At, B1); PG8_BAR; PG8_SCHED;
;             PG8_LDA(At, 1, 1); PG8_STAGE_NT(PG8_SB(1, 0), b3, voffB); PG8_STAGE_NT(PG8_SB(1, 1), b3 + hstepB, voffB); PG8_STAGE(PG8_SA(1, 0), a3, voffA);
;             PG8_WAIT_V(8); PG8_WAIT_L(0); PG8_BAR; PG8_MMA(1, 0, At, B0); PG8_MMA(1, 1, At, B1); PG8_BAR; PG8_SCHED;
	s_add_i32 s68, 0, 0x18000
	v_add_u32_e32 v140, s68, v219
	s_add_i32 s69, 0, 0x1c000
	ds_read_b128 v[104:107], v140
	ds_read_b128 v[116:119], v140 offset:1024
	ds_read_b128 v[128:131], v140 offset:2048
	ds_read_b128 v[140:143], v140 offset:3072
	v_add_u32_e32 v156, s69, v219
	ds_read_b128 v[144:147], v156
	ds_read_b128 v[148:151], v156 offset:1024
	ds_read_b128 v[152:155], v156 offset:2048
	ds_read_b128 v[156:159], v156 offset:3072
	s_add_u32 s50, s56, 0x104000
	s_addc_u32 s51, s57, 0
	s_mov_b32 m0, s22
	ds_read_b128 v[160:163], v223 offset:32768
	ds_read_b128 v[164:167], v223 offset:33792
	ds_read_b128 v[168:171], v223 offset:34816
	ds_read_b128 v[172:175], v223 offset:35840
	ds_read_b128 v[176:179], v223 offset:36864
	ds_read_b128 v[180:183], v223 offset:37888
	ds_read_b128 v[200:203], v223 offset:38912
	ds_read_b128 v[204:207], v223 offset:39936
	global_load_lds_dwordx4 v184, s[50:51]
	s_mov_b32 m0, s23
	s_nop 0
	global_load_lds_dwordx4 v188, s[50:51]
	s_waitcnt vmcnt(8)
	s_waitcnt lgkmcnt(0)
	s_barrier
	v_mfma_f32_16x16x32_bf16 v[136:139], v[104:107], v[160:163], v[136:139]
	v_mfma_f32_16x16x32_bf16 v[132:135], v[128:131], v[160:163], v[132:135]
	v_mfma_f32_16x16x32_bf16 v[112:115], v[104:107], v[168:171], v[112:115]
	v_mfma_f32_16x16x32_bf16 v[108:111], v[128:131], v[168:171], v[108:111]
	v_mfma_f32_16x16x32_bf16 v[92:95], v[104:107], v[176:179], v[92:95]
	v_mfma_f32_16x16x32_bf16 v[88:91], v[128:131], v[176:179], v[88:91]
	v_mfma_f32_16x16x32_bf16 v[76:79], v[104:107], v[200:203], v[76:79]
	v_mfma_f32_16x16x32_bf16 v[72:75], v[128:131], v[200:203], v[72:75]
	v_mfma_f32_16x16x32_bf16 v[136:139], v[116:119], v[164:167], v[136:139]
	v_mfma_f32_16x16x32_bf16 v[132:135], v[140:143], v[164:167], v[132:135]
	v_mfma_f32_16x16x32_bf16 v[112:115], v[116:119], v[172:175], v[112:115]
	v_mfma_f32_16x16x32_bf16 v[108:111], v[140:143], v[172:175], v[108:111]
	v_mfma_f32_16x16x32_bf16 v[92:95], v[116:119], v[180:183], v[92:95]
	v_mfma_f32_16x16x32_bf16 v[88:91], v[140:143], v[180:183], v[88:91]
	v_mfma_f32_16x16x32_bf16 v[76:79], v[116:119], v[204:207], v[76:79]
	v_mfma_f32_16x16x32_bf16 v[72:75], v[140:143], v[204:207], v[72:75]
	v_mfma_f32_16x16x32_bf16 v[124:127], v[144:147], v[160:163], v[124:127]
	v_mfma_f32_16x16x32_bf16 v[120:123], v[152:155], v[160:163], v[120:123]
	v_mfma_f32_16x16x32_bf16 v[100:103], v[144:147], v[168:171], v[100:103]
	v_mfma_f32_16x16x32_bf16 v[96:99], v[152:155], v[168:171], v[96:99]
	v_mfma_f32_16x16x32_bf16 v[84:87], v[144:147], v[176:179], v[84:87]
	v_mfma_f32_16x16x32_bf16 v[80:83], v[152:155], v[176:179], v[80:83]
	v_mfma_f32_16x16x32_bf16 v[68:71], v[144:147], v[200:203], v[68:71]
	v_mfma_f32_16x16x32_bf16 v[64:67], v[152:155], v[200:203], v[64:67]
	v_mfma_f32_16x16x32_bf16 v[124:127], v[148:151], v[164:167], v[124:127]
	v_mfma_f32_16x16x32_bf16 v[120:123], v[156:159], v[164:167], v[120:123]
	v_mfma_f32_16x16x32_bf16 v[100:103], v[148:151], v[172:175], v[100:103]
	v_mfma_f32_16x16x32_bf16 v[96:99], v[156:159], v[172:175], v[96:99]
	v_mfma_f32_16x16x32_bf16 v[84:87], v[148:151], v[180:183], v[84:87]
	v_mfma_f32_16x16x32_bf16 v[80:83], v[156:159], v[180:183], v[80:83]
	v_mfma_f32_16x16x32_bf16 v[68:71], v[148:151], v[204:207], v[68:71]
	v_mfma_f32_16x16x32_bf16 v[64:67], v[156:159], v[204:207], v[64:67]
	s_barrier
	s_add_i32 s50, s68, s9
	s_mov_b32 m0, s50
	s_add_u32 s98, s54, 0x80
	s_addc_u32 s99, s55, 0
	ds_read_b128 v[160:163], v223 offset:49152
	ds_read_b128 v[164:167], v223 offset:50176
	ds_read_b128 v[168:171], v223 offset:51200
	ds_read_b128 v[172:175], v223 offset:52224
	ds_read_b128 v[176:179], v223 offset:53248
	ds_read_b128 v[180:183], v223 offset:54272
	ds_read_b128 v[200:203], v223 offset:55296
	ds_read_b128 v[204:207], v223 offset:56320
	global_load_lds_dwordx4 v186, s[98:99]
	s_add_i32 m0, s50, 0x2000
	s_add_u32 s50, s54, 0x104080
	s_addc_u32 s51, s55, 0
	s_add_i32 s54, s69, s9
	global_load_lds_dwordx4 v190, s[98:99]
	s_mov_b32 m0, s54
	s_nop 0
	global_load_lds_dwordx4 v186, s[50:51]
	s_add_i32 m0, s54, 0x2000
	s_nop 0
	global_load_lds_dwordx4 v190, s[50:51]
	s_add_u32 s100, s56, 0x80
	s_addc_u32 s101, s57, 0
	s_mov_b32 m0, s25
	s_nop 0
	global_load_lds_dwordx4 v184, s[100:101]
	s_mov_b32 m0, s29
	s_nop 0
	global_load_lds_dwordx4 v188, s[100:101]
	s_waitcnt vmcnt(8)
	s_waitcnt lgkmcnt(0)
	s_barrier
	v_mfma_f32_16x16x32_bf16 v[60:63], v[104:107], v[160:163], v[60:63]
	v_mfma_f32_16x16x32_bf16 v[56:59], v[128:131], v[160:163], v[56:59]
	v_mfma_f32_16x16x32_bf16 v[44:47], v[104:107], v[168:171], v[44:47]
	v_mfma_f32_16x16x32_bf16 v[40:43], v[128:131], v[168:171], v[40:43]
	v_mfma_f32_16x16x32_bf16 v[28:31], v[104:107], v[176:179], v[28:31]
	v_mfma_f32_16x16x32_bf16 v[24:27], v[128:131], v[176:179], v[24:27]
	v_mfma_f32_16x16x32_bf16 v[12:15], v[104:107], v[200:203], v[12:15]
	v_mfma_f32_16x16x32_bf16 v[8:11], v[128:131], v[200:203], v[8:11]
	v_mfma_f32_16x16x32_bf16 v[60:63], v[116:119], v[164:167], v[60:63]
	v_mfma_f32_16x16x32_bf16 v[56:59], v[140:143], v[164:167], v[56:59]
	v_mfma_f32_16x16x32_bf16 v[44:47], v[116:119], v[172:175], v[44:47]
	v_mfma_f32_16x16x32_bf16 v[40:43], v[140:143], v[172:175], v[40:43]
	v_mfma_f32_16x16x32_bf16 v[28:31], v[116:119], v[180:183], v[28:31]
	v_mfma_f32_16x16x32_bf16 v[24:27], v[140:143], v[180:183], v[24:27]
	v_mfma_f32_16x16x32_bf16 v[12:15], v[116:119], v[204:207], v[12:15]
	v_mfma_f32_16x16x32_bf16 v[8:11], v[140:143], v[204:207], v[8:11]
	v_mfma_f32_16x16x32_bf16 v[52:55], v[144:147], v[160:163], v[52:55]
	v_mfma_f32_16x16x32_bf16 v[48:51], v[152:155], v[160:163], v[48:51]
	v_mfma_f32_16x16x32_bf16 v[36:39], v[144:147], v[168:171], v[36:39]
	v_mfma_f32_16x16x32_bf16 v[32:35], v[152:155], v[168:171], v[32:35]
	v_mfma_f32_16x16x32_bf16 v[20:23], v[144:147], v[176:179], v[20:23]
	v_mfma_f32_16x16x32_bf16 v[16:19], v[152:155], v[176:179], v[16:19]
	v_mfma_f32_16x16x32_bf16 v[4:7], v[144:147], v[200:203], v[4:7]
	v_mfma_f32_16x16x32_bf16 v[0:3], v[152:155], v[200:203], v[0:3]
	v_mfma_f32_16x16x32_bf16 v[52:55], v[148:151], v[164:167], v[52:55]
	v_mfma_f32_16x16x32_bf16 v[48:51], v[156:159], v[164:167], v[48:51]
	v_mfma_f32_16x16x32_bf16 v[36:39], v[148:151], v[172:175], v[36:39]
	v_mfma_f32_16x16x32_bf16 v[32:35], v[156:159], v[172:175], v[32:35]
	v_mfma_f32_16x16x32_bf16 v[20:23], v[148:151], v[180:183], v[20:23]
	v_mfma_f32_16x16x32_bf16 v[16:19], v[156:159], v[180:183], v[16:19]
	v_mfma_f32_16x16x32_bf16 v[4:7], v[148:151], v[204:207], v[4:7]
	v_mfma_f32_16x16x32_bf16 v[0:3], v[156:159], v[204:207], v[0:3]
	s_barrier
	s_add_i32 s67, s67, 2
	s_add_u32 s65, s65, 0x100
	s_addc_u32 s66, s66, 0
	s_cmp_gt_u32 s67, 61
	s_mov_b64 s[50:51], s[52:53]
	s_cbranch_scc0 .LBB0_1037
	s_and_b64 vcc, exec, s[46:47]
	s_cbranch_vccz .LBB0_1040
	s_barrier

; #define PG8_STAGE(bufoff, gbase, voff) do { _Pragma("unroll") for (int _i = 0; _i < 2; ++_i) \
;         __builtin_amdgcn_global_load_lds((const unsigned*)((const char*)(gbase) + (voff)[_i]), (PG8_LAS unsigned*)(lds + (bufoff) + ldsw + _i * 8192), 16, 0, 0); } while (0)
; #define PG8_STAGE_NT(bufoff, gbase, voff) do { _Pragma("unroll") for (int _i = 0; _i < 2; ++_i) \
;         __builtin_amdgcn_global_load_lds((const unsigned*)((const char*)(gbase) + (voff)[_i]), (PG8_LAS unsigned*)(lds + (bufoff) + ldsw + _i * 8192), 16, 0, PG8_B_AUX); } while (0)
; #define PG8_LDA(dst, b, h) do { _Pragma("unroll") for (int m = 0; m < 4; ++m) _Pragma("unroll") for (int k = 0; k < 2; ++k) dst[m][k] = *(const PG8_LAS bf16x8*)(lds + PG8_SA(b, h) + aoff + m * 2048 + k * 1024); } while (0)
; #define PG8_LDB(dst, b, h) do { _Pragma("unroll") for (int n = 0; n < 2; ++n) _Pragma("unroll") for (int k = 0; k < 2; ++k) dst[n][k] = *(const PG8_LAS bf16x8*)(lds + PG8_SB(b, h) + boff + n * 2048 + k * 1024); } while (0)
; #define PG8_MMA(ai, bj, At, Bt) do { __builtin_amdgcn_s_setprio(1); _Pragma("unroll") for (int m = 0; m < 4; ++m) _Pragma("unroll") for (int n = 0; n < 2; ++n) _Pragma("unroll") for (int k = 0; k < 2; ++k) \
;         acc[ai][bj][m][n] = __builtin_amdgcn_mfma_f32_16x16x32_bf16(Bt[n][k], At[m][k], acc[ai][bj][m][n], 0, 0, 0); __builtin_amdgcn_s_setprio(0); } while (0)
; #define PG8_WAIT_V(n) asm volatile("s_waitcnt vmcnt(" #n ")" ::: "memory")
; #define PG8_WAIT_L(n) asm volatile("s_waitcnt lgkmcnt(" #n ")" ::: "memory")
; #define PG8_BAR __builtin_amdgcn_s_barrier()
; #define PG8_SCHED __builtin_amdgcn_sched_barrier(0)
; template <class Epi, class Sched, bool ALIGN_EPI = false, bool SP2 = false>
; __device__ __forceinline__ void gemm_phase(PG8_LAS unsigned char* lds, const Gemm g, const Sched& S, const Epi& E, int wid) {
;     ...
;             PG8_LDB(B0, 0, 0); PG8_LDB(B1, 0, 1); PG8_SCHED; PG8_LDA(At, 0, 0); PG8_STAGE(PG8_SA(1, 1), a1 + hstepA, voffA);
;             PG8_WAIT_V(8); PG8_WAIT_L(0); PG8_BAR; PG8_MMA(0, 0, At, B0); PG8_MMA(0, 1, At, B1); PG8_BAR; PG8_SCHED;
;             PG8_LDA(At, 0, 1); PG8_STAGE_NT(PG8_SB(0, 0), b2, voffB); PG8_STAGE_NT(PG8_SB(0, 1), b2 + hstepB, voffB); PG8_STAGE(PG8_SA(0, 0), a2, voffA);
;             PG8_WAIT_V(8); PG8_WAIT_L(0); PG8_BAR; PG8_MMA(1, 0, At, B0); PG8_MMA(1, 1, At, B1); PG8_BAR; PG8_SCHED;
.LBB0_1133:
	ds_read_b128 v[144:147], v155
	ds_read_b128 v[148:151], v155 offset:1024
	ds_read_b128 v[160:163], v155 offset:2048
	ds_read_b128 v[164:167], v155 offset:3072
	ds_read_b128 v[168:171], v156
	ds_read_b128 v[172:175], v156 offset:1024
	ds_read_b128 v[176:179], v156 offset:2048
	ds_read_b128 v[180:183], v156 offset:3072
	s_add_u32 s4, s46, 0x100
	s_addc_u32 s5, s47, 0
	s_add_u32 s98, s46, 0x80
	s_addc_u32 s99, s47, 0
	s_add_u32 s100, s46, 0x104080
	s_addc_u32 s101, s47, 0
	s_cmp_eq_u32 s63, 60
	s_cselect_b32 s51, s43, s5
	s_cselect_b32 s50, s42, s4
	s_cselect_b32 s49, s45, s62
	s_cselect_b32 s48, s44, s61
	s_add_i32 m0, s22, 0xc000
	ds_read_b128 v[184:187], v157
	ds_read_b128 v[188:191], v157 offset:1024
	ds_read_b128 v[192:195], v157 offset:2048
	ds_read_b128 v[196:199], v157 offset:3072
	ds_read_b128 v[200:203], v157 offset:4096
	ds_read_b128 v[204:207], v157 offset:5120
	ds_read_b128 v[208:211], v157 offset:6144
	ds_read_b128 v[212:215], v157 offset:7168
	global_load_lds_dwordx4 v134, s[100:101]
	s_add_i32 m0, s22, 0xe000
	s_nop 0
	global_load_lds_dwordx4 v130, s[100:101]
	s_waitcnt vmcnt(8)
	s_waitcnt lgkmcnt(0)
	s_barrier
	v_mfma_f32_16x16x32_bf16 v[112:115], v[144:147], v[184:187], v[112:115]
	v_mfma_f32_16x16x32_bf16 v[108:111], v[160:163], v[184:187], v[108:111]
	v_mfma_f32_16x16x32_bf16 v[104:107], v[144:147], v[192:195], v[104:107]
	v_mfma_f32_16x16x32_bf16 v[100:103], v[160:163], v[192:195], v[100:103]
	v_mfma_f32_16x16x32_bf16 v[92:95], v[144:147], v[200:203], v[92:95]
	v_mfma_f32_16x16x32_bf16 v[84:87], v[160:163], v[200:203], v[84:87]
	v_mfma_f32_16x16x32_bf16 v[76:79], v[144:147], v[208:211], v[76:79]
	v_mfma_f32_16x16x32_bf16 v[68:71], v[160:163], v[208:211], v[68:71]
	v_mfma_f32_16x16x32_bf16 v[112:115], v[148:151], v[188:191], v[112:115]
	v_mfma_f32_16x16x32_bf16 v[108:111], v[164:167], v[188:191], v[108:111]
	v_mfma_f32_16x16x32_bf16 v[104:107], v[148:151], v[196:199], v[104:107]
	v_mfma_f32_16x16x32_bf16 v[100:103], v[164:167], v[196:199], v[100:103]
	v_mfma_f32_16x16x32_bf16 v[92:95], v[148:151], v[204:207], v[92:95]
	v_mfma_f32_16x16x32_bf16 v[84:87], v[164:167], v[204:207], v[84:87]
	v_mfma_f32_16x16x32_bf16 v[76:79], v[148:151], v[212:215], v[76:79]
	v_mfma_f32_16x16x32_bf16 v[68:71], v[164:167], v[212:215], v[68:71]
	v_mfma_f32_16x16x32_bf16 v[124:127], v[168:171], v[184:187], v[124:127]
	v_mfma_f32_16x16x32_bf16 v[120:123], v[176:179], v[184:187], v[120:123]
	v_mfma_f32_16x16x32_bf16 v[116:119], v[168:171], v[192:195], v[116:119]
	v_mfma_f32_16x16x32_bf16 v[96:99], v[176:179], v[192:195], v[96:99]
	v_mfma_f32_16x16x32_bf16 v[88:91], v[168:171], v[200:203], v[88:91]
	v_mfma_f32_16x16x32_bf16 v[80:83], v[176:179], v[200:203], v[80:83]
	v_mfma_f32_16x16x32_bf16 v[72:75], v[168:171], v[208:211], v[72:75]
	v_mfma_f32_16x16x32_bf16 v[64:67], v[176:179], v[208:211], v[64:67]
	v_mfma_f32_16x16x32_bf16 v[124:127], v[172:175], v[188:191], v[124:127]
	v_mfma_f32_16x16x32_bf16 v[120:123], v[180:183], v[188:191], v[120:123]
	v_mfma_f32_16x16x32_bf16 v[116:119], v[172:175], v[196:199], v[116:119]
	v_mfma_f32_16x16x32_bf16 v[96:99], v[180:183], v[196:199], v[96:99]
	v_mfma_f32_16x16x32_bf16 v[88:91], v[172:175], v[204:207], v[88:91]
	v_mfma_f32_16x16x32_bf16 v[80:83], v[180:183], v[204:207], v[80:83]
	v_mfma_f32_16x16x32_bf16 v[72:75], v[172:175], v[212:215], v[72:75]
	v_mfma_f32_16x16x32_bf16 v[64:67], v[180:183], v[212:215], v[64:67]
	s_barrier
	s_add_i32 s46, s55, s9
	s_mov_b32 m0, s46
	ds_read_b128 v[184:187], v157 offset:16384
	ds_read_b128 v[188:191], v157 offset:17408
	ds_read_b128 v[192:195], v157 offset:18432
	ds_read_b128 v[196:199], v157 offset:19456
	ds_read_b128 v[200:203], v157 offset:20480
	ds_read_b128 v[204:207], v157 offset:21504
	ds_read_b128 v[208:211], v157 offset:22528
	ds_read_b128 v[212:215], v157 offset:23552
	global_load_lds_dwordx4 v132, s[48:49]
	s_add_i32 m0, s46, 0x2000
	s_add_u32 s46, s48, 0x104000
	s_addc_u32 s47, s49, 0
	s_add_i32 s64, s56, s9
	global_load_lds_dwordx4 v128, s[48:49]
	s_mov_b32 m0, s64
	s_nop 0
	global_load_lds_dwordx4 v132, s[46:47]
	s_add_i32 m0, s64, 0x2000
	s_nop 0
	global_load_lds_dwordx4 v128, s[46:47]
	s_mov_b32 m0, s22
	s_nop 0
	global_load_lds_dwordx4 v134, s[50:51]
	s_mov_b32 m0, s23
	s_nop 0
	global_load_lds_dwordx4 v130, s[50:51]
	s_waitcnt vmcnt(8)
	s_waitcnt lgkmcnt(0)
	s_barrier
	v_mfma_f32_16x16x32_bf16 v[60:63], v[144:147], v[184:187], v[60:63]
	v_mfma_f32_16x16x32_bf16 v[52:55], v[160:163], v[184:187], v[52:55]
	v_mfma_f32_16x16x32_bf16 v[44:47], v[144:147], v[192:195], v[44:47]
	v_mfma_f32_16x16x32_bf16 v[36:39], v[160:163], v[192:195], v[36:39]
	v_mfma_f32_16x16x32_bf16 v[28:31], v[144:147], v[200:203], v[28:31]
	v_mfma_f32_16x16x32_bf16 v[20:23], v[160:163], v[200:203], v[20:23]
	v_mfma_f32_16x16x32_bf16 v[12:15], v[144:147], v[208:211], v[12:15]
	v_mfma_f32_16x16x32_bf16 v[4:7], v[160:163], v[208:211], v[4:7]
	v_mfma_f32_16x16x32_bf16 v[60:63], v[148:151], v[188:191], v[60:63]
	v_mfma_f32_16x16x32_bf16 v[52:55], v[164:167], v[188:191], v[52:55]
	v_mfma_f32_16x16x32_bf16 v[44:47], v[148:151], v[196:199], v[44:47]
	v_mfma_f32_16x16x32_bf16 v[36:39], v[164:167], v[196:199], v[36:39]
	v_mfma_f32_16x16x32_bf16 v[28:31], v[148:151], v[204:207], v[28:31]
	v_mfma_f32_16x16x32_bf16 v[20:23], v[164:167], v[204:207], v[20:23]
	v_mfma_f32_16x16x32_bf16 v[12:15], v[148:151], v[212:215], v[12:15]
	v_mfma_f32_16x16x32_bf16 v[4:7], v[164:167], v[212:215], v[4:7]
	v_mfma_f32_16x16x32_bf16 v[56:59], v[168:171], v[184:187], v[56:59]
	v_mfma_f32_16x16x32_bf16 v[48:51], v[176:179], v[184:187], v[48:51]
	v_mfma_f32_16x16x32_bf16 v[40:43], v[168:171], v[192:195], v[40:43]
	v_mfma_f32_16x16x32_bf16 v[32:35], v[176:179], v[192:195], v[32:35]
	v_mfma_f32_16x16x32_bf16 v[24:27], v[168:171], v[200:203], v[24:27]
	v_mfma_f32_16x16x32_bf16 v[16:19], v[176:179], v[200:203], v[16:19]
	v_mfma_f32_16x16x32_bf16 v[8:11], v[168:171], v[208:211], v[8:11]
	v_mfma_f32_16x16x32_bf16 v[0:3], v[176:179], v[208:211], v[0:3]
	v_mfma_f32_16x16x32_bf16 v[56:59], v[172:175], v[188:191], v[56:59]
	v_mfma_f32_16x16x32_bf16 v[48:51], v[180:183], v[188:191], v[48:51]
	v_mfma_f32_16x16x32_bf16 v[40:43], v[172:175], v[196:199], v[40:43]
	v_mfma_f32_16x16x32_bf16 v[32:35], v[180:183], v[196:199], v[32:35]
	v_mfma_f32_16x16x32_bf16 v[24:27], v[172:175], v[204:207], v[24:27]
	v_mfma_f32_16x16x32_bf16 v[16:19], v[180:183], v[204:207], v[16:19]
	v_mfma_f32_16x16x32_bf16 v[8:11], v[172:175], v[212:215], v[8:11]
	v_mfma_f32_16x16x32_bf16 v[0:3], v[180:183], v[212:215], v[0:3]
	s_barrier
; #define PG8_STAGE(bufoff, gbase, voff) do { _Pragma("unroll") for (int _i = 0; _i < 2; ++_i) \
;         __builtin_amdgcn_global_load_lds((const unsigned*)((const char*)(gbase) + (voff)[_i]), (PG8_LAS unsigned*)(lds + (bufoff) + ldsw + _i * 8192), 16, 0, 0); } while (0)
; #define PG8_STAGE_NT(bufoff, gbase, voff) do { _Pragma("unroll") for (int _i = 0; _i < 2; ++_i) \
;         __builtin_amdgcn_global_load_lds((const unsigned*)((const char*)(gbase) + (voff)[_i]), (PG8_LAS unsigned*)(lds + (bufoff) + ldsw + _i * 8192), 16, 0, PG8_B_AUX); } while (0)
; #define PG8_LDA(dst, b, h) do { _Pragma("unroll") for (int m = 0; m < 4; ++m) _Pragma("unroll") for (int k = 0; k < 2; ++k) dst[m][k] = *(const PG8_LAS bf16x8*)(lds + PG8_SA(b, h) + aoff + m * 2048 + k * 1024); } while (0)
; #define PG8_LDB(dst, b, h) do { _Pragma("unroll") for (int n = 0; n < 2; ++n) _Pragma("unroll") for (int k = 0; k < 2; ++k) dst[n][k] = *(const PG8_LAS bf16x8*)(lds + PG8_SB(b, h) + boff + n * 2048 + k * 1024); } while (0)
; #define PG8_MMA(ai, bj, At, Bt) do { __builtin_amdgcn_s_setprio(1); _Pragma("unroll") for (int m = 0; m < 4; ++m) _Pragma("unroll") for (int n = 0; n < 2; ++n) _Pragma("unroll") for (int k = 0; k < 2; ++k) \
;         acc[ai][bj][m][n] = __builtin_amdgcn_mfma_f32_16x16x32_bf16(Bt[n][k], At[m][k], acc[ai][bj][m][n], 0, 0, 0); __builtin_amdgcn_s_setprio(0); } while (0)
; #define PG8_WAIT_V(n) asm volatile("s_waitcnt vmcnt(" #n ")" ::: "memory")
; #define PG8_WAIT_L(n) asm volatile("s_waitcnt lgkmcnt(" #n ")" ::: "memory")
; #define PG8_BAR __builtin_amdgcn_s_barrier()
; #define PG8_SCHED __builtin_amdgcn_sched_barrier(0)
; template <class Epi, class Sched, bool ALIGN_EPI = false, bool SP2 = false>
; __device__ __forceinline__ void gemm_phase(PG8_LAS unsigned char* lds, const Gemm g, const Sched& S, const Epi& E, int wid) {
;     ...
;             PG8_LDB(B0, 1, 0); PG8_LDB(B1, 1, 1); PG8_SCHED; PG8_LDA(At, 1, 0); PG8_STAGE(PG8_SA(0, 1), a2 + hstepA, voffA);
;             PG8_WAIT_V(8); PG8_WAIT_L(0); PG8_BAR; PG8_MMA(0, 0, At, B0); PG8_MMA(0, 1, At, B1); PG8_BAR; PG8_SCHED;
;             PG8_LDA(At, 1, 1); PG8_STAGE_NT(PG8_SB(1, 0), b3, voffB); PG8_STAGE_NT(PG8_SB(1, 1), b3 + hstepB, voffB); PG8_STAGE(PG8_SA(1, 0), a3, voffA);
;             PG8_WAIT_V(8); PG8_WAIT_L(0); PG8_BAR; PG8_MMA(1, 0, At, B0); PG8_MMA(1, 1, At, B1); PG8_BAR; PG8_SCHED;
	s_add_i32 s64, 0, 0x18000
	v_add_u32_e32 v159, s64, v153
	s_add_i32 s65, 0, 0x1c000
	ds_read_b128 v[144:147], v159
	ds_read_b128 v[148:151], v159 offset:1024
	ds_read_b128 v[160:163], v159 offset:2048
	ds_read_b128 v[164:167], v159 offset:3072
	v_add_u32_e32 v159, s65, v153
	ds_read_b128 v[168:171], v159
	ds_read_b128 v[172:175], v159 offset:1024
	ds_read_b128 v[176:179], v159 offset:2048
	ds_read_b128 v[180:183], v159 offset:3072
	s_add_u32 s46, s50, 0x104000
	s_addc_u32 s47, s51, 0
	s_mov_b32 m0, s24
	ds_read_b128 v[184:187], v157 offset:32768
	ds_read_b128 v[188:191], v157 offset:33792
	ds_read_b128 v[192:195], v157 offset:34816
	ds_read_b128 v[196:199], v157 offset:35840
	ds_read_b128 v[200:203], v157 offset:36864
	ds_read_b128 v[204:207], v157 offset:37888
	ds_read_b128 v[208:211], v157 offset:38912
	ds_read_b128 v[212:215], v157 offset:39936
	global_load_lds_dwordx4 v134, s[46:47]
	s_mov_b32 m0, s25
	s_nop 0
	global_load_lds_dwordx4 v130, s[46:47]
	s_waitcnt vmcnt(8)
	s_waitcnt lgkmcnt(0)
	s_barrier
	v_mfma_f32_16x16x32_bf16 v[112:115], v[144:147], v[184:187], v[112:115]
	v_mfma_f32_16x16x32_bf16 v[108:111], v[160:163], v[184:187], v[108:111]
	v_mfma_f32_16x16x32_bf16 v[104:107], v[144:147], v[192:195], v[104:107]
	v_mfma_f32_16x16x32_bf16 v[100:103], v[160:163], v[192:195], v[100:103]
	v_mfma_f32_16x16x32_bf16 v[92:95], v[144:147], v[200:203], v[92:95]
	v_mfma_f32_16x16x32_bf16 v[84:87], v[160:163], v[200:203], v[84:87]
	v_mfma_f32_16x16x32_bf16 v[76:79], v[144:147], v[208:211], v[76:79]
	v_mfma_f32_16x16x32_bf16 v[68:71], v[160:163], v[208:211], v[68:71]
	v_mfma_f32_16x16x32_bf16 v[112:115], v[148:151], v[188:191], v[112:115]
	v_mfma_f32_16x16x32_bf16 v[108:111], v[164:167], v[188:191], v[108:111]
	v_mfma_f32_16x16x32_bf16 v[104:107], v[148:151], v[196:199], v[104:107]
	v_mfma_f32_16x16x32_bf16 v[100:103], v[164:167], v[196:199], v[100:103]
	v_mfma_f32_16x16x32_bf16 v[92:95], v[148:151], v[204:207], v[92:95]
	v_mfma_f32_16x16x32_bf16 v[84:87], v[164:167], v[204:207], v[84:87]
	v_mfma_f32_16x16x32_bf16 v[76:79], v[148:151], v[212:215], v[76:79]
	v_mfma_f32_16x16x32_bf16 v[68:71], v[164:167], v[212:215], v[68:71]
	v_mfma_f32_16x16x32_bf16 v[124:127], v[168:171], v[184:187], v[124:127]
	v_mfma_f32_16x16x32_bf16 v[120:123], v[176:179], v[184:187], v[120:123]
	v_mfma_f32_16x16x32_bf16 v[116:119], v[168:171], v[192:195], v[116:119]
	v_mfma_f32_16x16x32_bf16 v[96:99], v[176:179], v[192:195], v[96:99]
	v_mfma_f32_16x16x32_bf16 v[88:91], v[168:171], v[200:203], v[88:91]
	v_mfma_f32_16x16x32_bf16 v[80:83], v[176:179], v[200:203], v[80:83]
	v_mfma_f32_16x16x32_bf16 v[72:75], v[168:171], v[208:211], v[72:75]
	v_mfma_f32_16x16x32_bf16 v[64:67], v[176:179], v[208:211], v[64:67]
	v_mfma_f32_16x16x32_bf16 v[124:127], v[172:175], v[188:191], v[124:127]
	v_mfma_f32_16x16x32_bf16 v[120:123], v[180:183], v[188:191], v[120:123]
	v_mfma_f32_16x16x32_bf16 v[116:119], v[172:175], v[196:199], v[116:119]
	v_mfma_f32_16x16x32_bf16 v[96:99], v[180:183], v[196:199], v[96:99]
	v_mfma_f32_16x16x32_bf16 v[88:91], v[172:175], v[204:207], v[88:91]
	v_mfma_f32_16x16x32_bf16 v[80:83], v[180:183], v[204:207], v[80:83]
	v_mfma_f32_16x16x32_bf16 v[72:75], v[172:175], v[212:215], v[72:75]
	v_mfma_f32_16x16x32_bf16 v[64:67], v[180:183], v[212:215], v[64:67]
	s_barrier
	s_add_i32 s46, s64, s9
	s_mov_b32 m0, s46
	s_add_u32 s98, s48, 0x80
	s_addc_u32 s99, s49, 0
	ds_read_b128 v[184:187], v157 offset:49152
	ds_read_b128 v[188:191], v157 offset:50176
	ds_read_b128 v[192:195], v157 offset:51200
	ds_read_b128 v[196:199], v157 offset:52224
	ds_read_b128 v[200:203], v157 offset:53248
	ds_read_b128 v[204:207], v157 offset:54272
	ds_read_b128 v[208:211], v157 offset:55296
	ds_read_b128 v[212:215], v157 offset:56320
	global_load_lds_dwordx4 v132, s[98:99]
	s_add_i32 m0, s46, 0x2000
	s_add_u32 s46, s48, 0x104080
	s_addc_u32 s47, s49, 0
	s_add_i32 s48, s65, s9
	global_load_lds_dwordx4 v128, s[98:99]
	s_mov_b32 m0, s48
	s_nop 0
	global_load_lds_dwordx4 v132, s[46:47]
	s_add_i32 m0, s48, 0x2000
	s_nop 0
	global_load_lds_dwordx4 v128, s[46:47]
	s_add_u32 s100, s50, 0x80
	s_addc_u32 s101, s51, 0
	s_mov_b32 m0, s52
	s_nop 0
	global_load_lds_dwordx4 v134, s[100:101]
	s_mov_b32 m0, s53
	s_nop 0
	global_load_lds_dwordx4 v130, s[100:101]
	s_waitcnt vmcnt(8)
	s_waitcnt lgkmcnt(0)
	s_barrier
	v_mfma_f32_16x16x32_bf16 v[60:63], v[144:147], v[184:187], v[60:63]
	v_mfma_f32_16x16x32_bf16 v[52:55], v[160:163], v[184:187], v[52:55]
	v_mfma_f32_16x16x32_bf16 v[44:47], v[144:147], v[192:195], v[44:47]
	v_mfma_f32_16x16x32_bf16 v[36:39], v[160:163], v[192:195], v[36:39]
	v_mfma_f32_16x16x32_bf16 v[28:31], v[144:147], v[200:203], v[28:31]
	v_mfma_f32_16x16x32_bf16 v[20:23], v[160:163], v[200:203], v[20:23]
	v_mfma_f32_16x16x32_bf16 v[12:15], v[144:147], v[208:211], v[12:15]
	v_mfma_f32_16x16x32_bf16 v[4:7], v[160:163], v[208:211], v[4:7]
	v_mfma_f32_16x16x32_bf16 v[60:63], v[148:151], v[188:191], v[60:63]
	v_mfma_f32_16x16x32_bf16 v[52:55], v[164:167], v[188:191], v[52:55]
	v_mfma_f32_16x16x32_bf16 v[44:47], v[148:151], v[196:199], v[44:47]
	v_mfma_f32_16x16x32_bf16 v[36:39], v[164:167], v[196:199], v[36:39]
	v_mfma_f32_16x16x32_bf16 v[28:31], v[148:151], v[204:207], v[28:31]
	v_mfma_f32_16x16x32_bf16 v[20:23], v[164:167], v[204:207], v[20:23]
	v_mfma_f32_16x16x32_bf16 v[12:15], v[148:151], v[212:215], v[12:15]
	v_mfma_f32_16x16x32_bf16 v[4:7], v[164:167], v[212:215], v[4:7]
	v_mfma_f32_16x16x32_bf16 v[56:59], v[168:171], v[184:187], v[56:59]
	v_mfma_f32_16x16x32_bf16 v[48:51], v[176:179], v[184:187], v[48:51]
	v_mfma_f32_16x16x32_bf16 v[40:43], v[168:171], v[192:195], v[40:43]
	v_mfma_f32_16x16x32_bf16 v[32:35], v[176:179], v[192:195], v[32:35]
	v_mfma_f32_16x16x32_bf16 v[24:27], v[168:171], v[200:203], v[24:27]
	v_mfma_f32_16x16x32_bf16 v[16:19], v[176:179], v[200:203], v[16:19]
	v_mfma_f32_16x16x32_bf16 v[8:11], v[168:171], v[208:211], v[8:11]
	v_mfma_f32_16x16x32_bf16 v[0:3], v[176:179], v[208:211], v[0:3]
	v_mfma_f32_16x16x32_bf16 v[56:59], v[172:175], v[188:191], v[56:59]
	v_mfma_f32_16x16x32_bf16 v[48:51], v[180:183], v[188:191], v[48:51]
	v_mfma_f32_16x16x32_bf16 v[40:43], v[172:175], v[196:199], v[40:43]
	v_mfma_f32_16x16x32_bf16 v[32:35], v[180:183], v[196:199], v[32:35]
	v_mfma_f32_16x16x32_bf16 v[24:27], v[172:175], v[204:207], v[24:27]
	v_mfma_f32_16x16x32_bf16 v[16:19], v[180:183], v[204:207], v[16:19]
	v_mfma_f32_16x16x32_bf16 v[8:11], v[172:175], v[212:215], v[8:11]
	v_mfma_f32_16x16x32_bf16 v[0:3], v[180:183], v[212:215], v[0:3]
	s_barrier
	s_add_i32 s63, s63, 2
	s_add_u32 s61, s61, 0x100
	s_addc_u32 s62, s62, 0
	s_cmp_gt_u32 s63, 61
	s_mov_b64 s[46:47], s[4:5]
	s_cbranch_scc0 .LBB0_1133
	s_and_b64 vcc, exec, s[40:41]
	s_cbranch_vccz .LBB0_1136
	s_barrier
